# row-sum accumulation with v_pk_add_f32 (same summation order) in both attention loops
# baseline (speedup 1.0000x reference)
.LBB0_318:
	v_and_b32_e32 v131, 63, v16
	v_lshlrev_b32_e32 v0, 4, v136
	v_lshlrev_b32_e32 v30, 8, v136
	v_and_b32_e32 v31, 0xf0, v0
	v_or_b32_e32 v21, s4, v130
	v_bitop3_b32 v149, v21, v30, v31 bitop3:0xde
	v_or_b32_e32 v22, 32, v21
	v_bitop3_b32 v148, v22, v30, v31 bitop3:0xde
	v_or_b32_e32 v22, 64, v21
	v_bitop3_b32 v143, v22, v30, v31 bitop3:0xde
	v_or_b32_e32 v22, 0x60, v21
	v_bitop3_b32 v141, v22, v30, v31 bitop3:0xde
	v_add_u32_e32 v149, s38, v149
	v_add_u32_e32 v148, s38, v148
	v_add_u32_e32 v143, s38, v143
	v_add_u32_e32 v141, s38, v141
	v_lshlrev_b32_e32 v34, 4, v131
	v_lshlrev_b32_e32 v33, 3, v131
	v_and_b32_e32 v22, 0xc0, v34
	v_and_or_b32 v34, v33, 24, v22
	v_lshlrev_b32_e32 v26, 1, v131
	v_and_b32_e32 v30, 32, v26
	v_and_b32_e32 v33, 0x100, v33
	v_or3_b32 v140, v34, v30, v33
	v_mov_b32_e32 v151, v140
	v_add3_u32 v0, v18, v20, s45
	v_ashrrev_i32_e32 v1, 31, v0
	v_lshlrev_b64 v[0:1], 13, v[0:1]
	v_and_b32_e32 v2, 3, v16
	v_lshl_add_u64 v[0:1], s[10:11], 0, v[0:1]
	v_lshlrev_b32_e32 v2, 4, v2
	v_mov_b32_e32 v3, v129
	v_lshl_add_u64 v[0:1], v[0:1], 0, v[2:3]
	v_add_lshl_u32 v2, s44, v19, 1
	v_lshl_add_u64 v[0:1], v[0:1], 0, v[2:3]
	v_lshl_add_u64 v[132:133], s[28:29], 0, v[0:1]
	v_add_u32_e32 v0, s5, v17
	v_ashrrev_i32_e32 v1, 31, v0
	v_lshlrev_b64 v[0:1], 13, v[0:1]
	v_lshl_add_u64 v[0:1], s[10:11], 0, v[0:1]
	v_lshl_add_u64 v[0:1], v[0:1], 0, v[128:129]
	v_lshl_add_u64 v[134:135], s[28:29], 0, v[0:1]
	v_lshl_add_u64 v[132:133], v[132:133], 0, s[16:17]
	v_lshl_add_u64 v[134:135], v[134:135], 0, s[16:17]
	v_add3_u32 v0, v18, v20, s45
	v_lshlrev_b32_e32 v0, 13, v0
	v_and_b32_e32 v2, 3, v16
	v_lshl_add_u32 v0, v2, 4, v0
	v_add_lshl_u32 v2, s44, v19, 1
	v_add_u32_e32 v150, v0, v2
	v_add_u32_e32 v0, s5, v17
	v_lshl_add_u32 v142, v0, 13, v128
	s_add_u32 s72, s28, s10
	s_addc_u32 s73, s29, s11
	s_add_u32 s72, s72, s16
	s_addc_u32 s73, s73, s17
	s_mov_b32 s46, s72
	s_mov_b32 s47, s73
	s_mov_b32 s62, 0
	s_add_i32 s71, s41, 0x2000
	s_movk_i32 s70, 31
	v_mov_b32_e32 v0, 0
	v_mov_b32_e32 v1, 0
	v_mov_b32_e32 v2, 0
	v_mov_b32_e32 v3, 0
	v_mov_b32_e32 v4, 0
	v_mov_b32_e32 v5, 0
	v_mov_b32_e32 v6, 0
	v_mov_b32_e32 v7, 0
	v_mov_b32_e32 v8, 0
	v_mov_b32_e32 v9, 0
	v_mov_b32_e32 v10, 0
	v_mov_b32_e32 v11, 0
	v_mov_b32_e32 v12, 0
	v_mov_b32_e32 v13, 0
	v_mov_b32_e32 v14, 0
	v_mov_b32_e32 v15, 0
	v_mov_b32_e32 v16, 0
	v_mov_b32_e32 v17, 0
	v_mov_b32_e32 v18, 0
	v_mov_b32_e32 v19, 0
	v_mov_b32_e32 v20, 0
	v_mov_b32_e32 v21, 0
	v_mov_b32_e32 v22, 0
	v_mov_b32_e32 v23, 0
	v_mov_b32_e32 v24, 0
	v_mov_b32_e32 v25, 0
	v_mov_b32_e32 v26, 0
	v_mov_b32_e32 v27, 0
	v_mov_b32_e32 v28, 0
	v_mov_b32_e32 v29, 0
	v_mov_b32_e32 v30, 0
	v_mov_b32_e32 v31, 0
	v_mov_b32_e32 v32, 0
	v_mov_b32_e32 v33, 0
	v_mov_b32_e32 v34, 0
	v_mov_b32_e32 v35, 0
	v_mov_b32_e32 v36, 0
	v_mov_b32_e32 v37, 0
	v_mov_b32_e32 v38, 0
	v_mov_b32_e32 v39, 0
	v_mov_b32_e32 v40, 0
	v_mov_b32_e32 v41, 0
	v_mov_b32_e32 v42, 0
	v_mov_b32_e32 v43, 0
	v_mov_b32_e32 v44, 0
	v_mov_b32_e32 v45, 0
	v_mov_b32_e32 v46, 0
	v_mov_b32_e32 v47, 0
	v_mov_b32_e32 v48, 0
	v_mov_b32_e32 v49, 0
	v_mov_b32_e32 v50, 0
	v_mov_b32_e32 v51, 0
	v_mov_b32_e32 v52, 0
	v_mov_b32_e32 v53, 0
	v_mov_b32_e32 v54, 0
	v_mov_b32_e32 v55, 0
	v_mov_b32_e32 v56, 0
	v_mov_b32_e32 v57, 0
	v_mov_b32_e32 v58, 0
	v_mov_b32_e32 v59, 0
	v_mov_b32_e32 v60, 0
	v_mov_b32_e32 v61, 0
	v_mov_b32_e32 v62, 0
	v_mov_b32_e32 v63, 0
	v_mov_b32_e32 v234, 0
	v_mov_b32_e32 v235, 0
	s_waitcnt vmcnt(0)
	s_barrier
	ds_read_b128 v[194:197], v149 offset:0
	ds_read_b128 v[198:201], v148 offset:0
	ds_read_b128 v[202:205], v143 offset:0
	ds_read_b128 v[206:209], v141 offset:0
	ds_read_b128 v[210:213], v149 offset:8192
	ds_read_b128 v[214:217], v148 offset:8192
	ds_read_b128 v[218:221], v143 offset:8192
	ds_read_b128 v[222:225], v141 offset:8192
	s_waitcnt lgkmcnt(7)
	v_mfma_f32_32x32x16_bf16 v[64:79], v[194:197], v[124:127], 0
	s_waitcnt lgkmcnt(6)
	v_mfma_f32_32x32x16_bf16 v[64:79], v[198:201], v[120:123], v[64:79]
	s_waitcnt lgkmcnt(5)
	v_mfma_f32_32x32x16_bf16 v[64:79], v[202:205], v[116:119], v[64:79]
	s_waitcnt lgkmcnt(4)
	v_mfma_f32_32x32x16_bf16 v[64:79], v[206:209], v[112:115], v[64:79]
	s_waitcnt lgkmcnt(3)
	v_mfma_f32_32x32x16_bf16 v[80:95], v[210:213], v[124:127], 0
	s_waitcnt lgkmcnt(2)
	v_mfma_f32_32x32x16_bf16 v[80:95], v[214:217], v[120:123], v[80:95]
	s_waitcnt lgkmcnt(1)
	v_mfma_f32_32x32x16_bf16 v[80:95], v[218:221], v[116:119], v[80:95]
	s_waitcnt lgkmcnt(0)
	v_mfma_f32_32x32x16_bf16 v[80:95], v[222:225], v[112:115], v[80:95]
	s_nop 3
	v_exp_f32_e32 v64, v64
	v_exp_f32_e32 v65, v65
	ds_read_b128 v[194:197], v149 offset:16384
	v_exp_f32_e32 v66, v66
	v_exp_f32_e32 v67, v67
	v_pk_add_f32 v[234:235], v[234:235], v[64:65]
	ds_read_b128 v[198:201], v148 offset:16384
	v_exp_f32_e32 v68, v68
	v_exp_f32_e32 v69, v69
	v_pk_add_f32 v[234:235], v[234:235], v[66:67]
	ds_read_b128 v[202:205], v143 offset:16384
	v_exp_f32_e32 v70, v70
	v_exp_f32_e32 v71, v71
	v_pk_add_f32 v[234:235], v[234:235], v[68:69]
	ds_read_b128 v[206:209], v141 offset:16384
	v_pk_add_f32 v[234:235], v[234:235], v[70:71]
	v_cvt_pk_bf16_f32 v178, v64, v65
	v_cvt_pk_bf16_f32 v180, v68, v69
	ds_read_b128 v[210:213], v149 offset:24576
	v_cvt_pk_bf16_f32 v179, v66, v67
	v_cvt_pk_bf16_f32 v181, v70, v71
	ds_read_b128 v[214:217], v148 offset:24576
.Lda_loop:
	s_waitcnt lgkmcnt(5)
	v_mfma_f32_32x32x16_bf16 v[96:111], v[194:197], v[124:127], 0
	v_exp_f32_e32 v72, v72
	v_exp_f32_e32 v73, v73
	ds_read_b128 v[218:221], v143 offset:24576
	s_waitcnt lgkmcnt(5)
	v_mfma_f32_32x32x16_bf16 v[96:111], v[198:201], v[120:123], v[96:111]
	v_exp_f32_e32 v74, v74
	v_exp_f32_e32 v75, v75
	v_pk_add_f32 v[234:235], v[234:235], v[72:73]
	ds_read_b128 v[222:225], v141 offset:24576
	ds_read_b64_tr_b16 v[226:227], v151 offset:0
	ds_read_b64_tr_b16 v[228:229], v151 offset:2048
	s_waitcnt lgkmcnt(7)
	v_mfma_f32_32x32x16_bf16 v[96:111], v[202:205], v[116:119], v[96:111]
	v_exp_f32_e32 v76, v76
	v_exp_f32_e32 v77, v77
	v_pk_add_f32 v[234:235], v[234:235], v[74:75]
	ds_read_b64_tr_b16 v[230:231], v151 offset:512
	ds_read_b64_tr_b16 v[232:233], v151 offset:2560
	s_waitcnt lgkmcnt(8)
	v_mfma_f32_32x32x16_bf16 v[96:111], v[206:209], v[112:115], v[96:111]
	v_exp_f32_e32 v78, v78
	v_exp_f32_e32 v79, v79
	v_pk_add_f32 v[234:235], v[234:235], v[76:77]
	ds_read_b64_tr_b16 v[238:239], v151 offset:1024
	ds_read_b64_tr_b16 v[240:241], v151 offset:3072
	s_waitcnt lgkmcnt(9)
	v_mfma_f32_32x32x16_bf16 v[162:177], v[210:213], v[124:127], 0
	v_pk_add_f32 v[234:235], v[234:235], v[78:79]
	v_cvt_pk_bf16_f32 v182, v72, v73
	v_cvt_pk_bf16_f32 v184, v76, v77
	ds_read_b64_tr_b16 v[242:243], v151 offset:1536
	ds_read_b64_tr_b16 v[244:245], v151 offset:3584
	s_waitcnt lgkmcnt(10)
	v_mfma_f32_32x32x16_bf16 v[162:177], v[214:217], v[120:123], v[162:177]
	v_cvt_pk_bf16_f32 v183, v74, v75
	v_cvt_pk_bf16_f32 v185, v78, v79
	ds_read_b64_tr_b16 v[246:247], v151 offset:4096
	ds_read_b64_tr_b16 v[248:249], v151 offset:6144
	s_waitcnt lgkmcnt(11)
	v_mfma_f32_32x32x16_bf16 v[162:177], v[218:221], v[116:119], v[162:177]
	v_exp_f32_e32 v80, v80
	v_exp_f32_e32 v81, v81
	ds_read_b64_tr_b16 v[250:251], v151 offset:4608
	ds_read_b64_tr_b16 v[252:253], v151 offset:6656
	s_waitcnt lgkmcnt(12)
	v_mfma_f32_32x32x16_bf16 v[162:177], v[222:225], v[112:115], v[162:177]
	v_exp_f32_e32 v82, v82
	v_exp_f32_e32 v83, v83
	v_pk_add_f32 v[234:235], v[234:235], v[80:81]
	ds_read_b64_tr_b16 v[152:153], v151 offset:5120
	ds_read_b64_tr_b16 v[154:155], v151 offset:7168
	s_waitcnt lgkmcnt(12)
	v_mfma_f32_32x32x16_bf16 v[48:63], v[178:181], v[226:229], v[48:63]
	v_exp_f32_e32 v84, v84
	v_exp_f32_e32 v85, v85
	v_pk_add_f32 v[234:235], v[234:235], v[82:83]
	ds_read_b64_tr_b16 v[226:227], v151 offset:5632
	ds_read_b64_tr_b16 v[228:229], v151 offset:7680
	s_waitcnt lgkmcnt(12)
	v_mfma_f32_32x32x16_bf16 v[32:47], v[178:181], v[230:233], v[32:47]
	v_exp_f32_e32 v86, v86
	v_exp_f32_e32 v87, v87
	v_pk_add_f32 v[234:235], v[234:235], v[84:85]
	ds_read_b64_tr_b16 v[230:231], v151 offset:8192
	ds_read_b64_tr_b16 v[232:233], v151 offset:10240
	s_waitcnt lgkmcnt(12)
	v_mfma_f32_32x32x16_bf16 v[16:31], v[178:181], v[238:241], v[16:31]
	v_pk_add_f32 v[234:235], v[234:235], v[86:87]
	v_cvt_pk_bf16_f32 v186, v80, v81
	v_cvt_pk_bf16_f32 v188, v84, v85
	ds_read_b64_tr_b16 v[238:239], v151 offset:8704
	ds_read_b64_tr_b16 v[240:241], v151 offset:10752
	s_waitcnt lgkmcnt(12)
	v_mfma_f32_32x32x16_bf16 v[0:15], v[178:181], v[242:245], v[0:15]
	v_cvt_pk_bf16_f32 v187, v82, v83
	v_cvt_pk_bf16_f32 v189, v86, v87
	ds_read_b64_tr_b16 v[242:243], v151 offset:9216
	ds_read_b64_tr_b16 v[244:245], v151 offset:11264
	s_waitcnt lgkmcnt(12)
	v_mfma_f32_32x32x16_bf16 v[48:63], v[182:185], v[246:249], v[48:63]
	v_exp_f32_e32 v88, v88
	v_exp_f32_e32 v89, v89
	ds_read_b64_tr_b16 v[246:247], v151 offset:9728
	ds_read_b64_tr_b16 v[248:249], v151 offset:11776
	s_waitcnt lgkmcnt(12)
	v_mfma_f32_32x32x16_bf16 v[32:47], v[182:185], v[250:253], v[32:47]
	v_exp_f32_e32 v90, v90
	v_exp_f32_e32 v91, v91
	v_pk_add_f32 v[234:235], v[234:235], v[88:89]
	ds_read_b64_tr_b16 v[250:251], v151 offset:12288
	ds_read_b64_tr_b16 v[252:253], v151 offset:14336
	s_waitcnt lgkmcnt(12)
	v_mfma_f32_32x32x16_bf16 v[16:31], v[182:185], v[152:155], v[16:31]
	v_exp_f32_e32 v92, v92
	v_exp_f32_e32 v93, v93
	v_pk_add_f32 v[234:235], v[234:235], v[90:91]
	ds_read_b64_tr_b16 v[152:153], v151 offset:12800
	ds_read_b64_tr_b16 v[154:155], v151 offset:14848
	s_waitcnt lgkmcnt(12)
	v_mfma_f32_32x32x16_bf16 v[0:15], v[182:185], v[226:229], v[0:15]
	v_exp_f32_e32 v94, v94
	v_exp_f32_e32 v95, v95
	v_pk_add_f32 v[234:235], v[234:235], v[92:93]
	ds_read_b64_tr_b16 v[226:227], v151 offset:13312
	ds_read_b64_tr_b16 v[228:229], v151 offset:15360
	s_waitcnt lgkmcnt(12)
	v_mfma_f32_32x32x16_bf16 v[48:63], v[186:189], v[230:233], v[48:63]
	v_pk_add_f32 v[234:235], v[234:235], v[94:95]
	v_cvt_pk_bf16_f32 v190, v88, v89
	v_cvt_pk_bf16_f32 v192, v92, v93
	ds_read_b64_tr_b16 v[230:231], v151 offset:13824
	ds_read_b64_tr_b16 v[232:233], v151 offset:15872
	s_waitcnt lgkmcnt(12)
	v_mfma_f32_32x32x16_bf16 v[32:47], v[186:189], v[238:241], v[32:47]
	s_waitcnt vmcnt(0)
	s_barrier
	s_add_i32 s63, s62, 0xc000
	s_cmp_ge_u32 s63, 0x14000
	s_cselect_b32 s69, 0x14000, 0
	s_sub_i32 s63, s63, s69
	s_add_i32 s68, s62, 0x10000
	s_cmp_ge_u32 s68, 0x14000
	s_cselect_b32 s69, 0x14000, 0
	s_sub_i32 s68, s68, s69
	s_add_i32 s62, s62, 0x4000
	s_cmp_ge_u32 s62, 0x14000
	s_cselect_b32 s69, 0x14000, 0
	s_sub_i32 s62, s62, s69
	v_add_u32_e32 v151, s62, v140
	v_cvt_pk_bf16_f32 v191, v90, v91
	v_cvt_pk_bf16_f32 v193, v94, v95
	s_add_i32 m0, s41, s63
	s_add_u32 s42, s46, 0x5d81000
	s_addc_u32 s43, s47, 0
	global_load_lds_dwordx4 v150, s[42:43]
	s_waitcnt lgkmcnt(10)
	v_mfma_f32_32x32x16_bf16 v[16:31], v[186:189], v[242:245], v[16:31]
	v_exp_f32_e32 v96, v96
	v_exp_f32_e32 v97, v97
	ds_read_b128 v[194:197], v149 offset:32768
	s_add_i32 m0, s71, s63
	s_add_u32 s42, s46, 0x5dc1000
	s_addc_u32 s43, s47, 0
	global_load_lds_dwordx4 v150, s[42:43]
	s_waitcnt lgkmcnt(9)
	v_mfma_f32_32x32x16_bf16 v[0:15], v[186:189], v[246:249], v[0:15]
	v_exp_f32_e32 v98, v98
	v_exp_f32_e32 v99, v99
	v_pk_add_f32 v[234:235], v[234:235], v[96:97]
	ds_read_b128 v[198:201], v148 offset:32768
	s_add_i32 m0, s40, 0x0
	s_add_u32 s42, s72, 0x5e00800
	s_addc_u32 s43, s73, 0
	global_load_lds_dwordx4 v142, s[42:43]
	s_waitcnt lgkmcnt(8)
	v_mfma_f32_32x32x16_bf16 v[48:63], v[190:193], v[250:253], v[48:63]
	v_exp_f32_e32 v100, v100
	v_exp_f32_e32 v101, v101
	v_pk_add_f32 v[234:235], v[234:235], v[98:99]
	ds_read_b128 v[202:205], v143 offset:32768
	s_add_i32 m0, s40, 0x2000
	s_add_u32 s42, s72, 0x5e40800
	s_addc_u32 s43, s73, 0
	global_load_lds_dwordx4 v142, s[42:43]
	s_waitcnt lgkmcnt(7)
	v_mfma_f32_32x32x16_bf16 v[32:47], v[190:193], v[152:155], v[32:47]
	v_exp_f32_e32 v102, v102
	v_exp_f32_e32 v103, v103
	v_pk_add_f32 v[234:235], v[234:235], v[100:101]
	ds_read_b128 v[206:209], v141 offset:32768
	s_add_i32 m0, s41, s68
	s_add_u32 s42, s46, 0x5e01000
	s_addc_u32 s43, s47, 0
	global_load_lds_dwordx4 v150, s[42:43]
	s_waitcnt lgkmcnt(6)
	v_mfma_f32_32x32x16_bf16 v[16:31], v[190:193], v[226:229], v[16:31]
	v_pk_add_f32 v[234:235], v[234:235], v[102:103]
	v_cvt_pk_bf16_f32 v178, v96, v97
	v_cvt_pk_bf16_f32 v180, v100, v101
	ds_read_b128 v[210:213], v149 offset:40960
	s_add_i32 m0, s71, s68
	s_add_u32 s42, s46, 0x5e41000
	s_addc_u32 s43, s47, 0
	global_load_lds_dwordx4 v150, s[42:43]
	s_waitcnt lgkmcnt(5)
	v_mfma_f32_32x32x16_bf16 v[0:15], v[190:193], v[230:233], v[0:15]
	v_cvt_pk_bf16_f32 v179, v98, v99
	v_cvt_pk_bf16_f32 v181, v102, v103
	ds_read_b128 v[214:217], v148 offset:40960
	s_add_i32 m0, s40, 0x4000
	s_add_u32 s42, s72, 0x5e80800
	s_addc_u32 s43, s73, 0
	global_load_lds_dwordx4 v142, s[42:43]
	s_add_i32 m0, s40, 0x6000
	s_add_u32 s42, s72, 0x5ec0800
	s_addc_u32 s43, s73, 0
	global_load_lds_dwordx4 v142, s[42:43]
	s_add_u32 s72, s72, 0x100000
	s_addc_u32 s73, s73, 0
	s_add_u32 s46, s46, 0x100000
	s_addc_u32 s47, s47, 0
	s_waitcnt lgkmcnt(5)
	v_mfma_f32_32x32x16_bf16 v[64:79], v[194:197], v[124:127], 0
	v_exp_f32_e32 v104, v104
	v_exp_f32_e32 v105, v105
	ds_read_b128 v[218:221], v143 offset:40960
	s_waitcnt lgkmcnt(5)
	v_mfma_f32_32x32x16_bf16 v[64:79], v[198:201], v[120:123], v[64:79]
	v_exp_f32_e32 v106, v106
	v_exp_f32_e32 v107, v107
	v_pk_add_f32 v[234:235], v[234:235], v[104:105]
	ds_read_b128 v[222:225], v141 offset:40960
	ds_read_b64_tr_b16 v[226:227], v151 offset:0
	ds_read_b64_tr_b16 v[228:229], v151 offset:2048
	s_waitcnt lgkmcnt(7)
	v_mfma_f32_32x32x16_bf16 v[64:79], v[202:205], v[116:119], v[64:79]
	v_exp_f32_e32 v108, v108
	v_exp_f32_e32 v109, v109
	v_pk_add_f32 v[234:235], v[234:235], v[106:107]
	ds_read_b64_tr_b16 v[230:231], v151 offset:512
	ds_read_b64_tr_b16 v[232:233], v151 offset:2560
	s_waitcnt lgkmcnt(8)
	v_mfma_f32_32x32x16_bf16 v[64:79], v[206:209], v[112:115], v[64:79]
	v_exp_f32_e32 v110, v110
	v_exp_f32_e32 v111, v111
	v_pk_add_f32 v[234:235], v[234:235], v[108:109]
	ds_read_b64_tr_b16 v[238:239], v151 offset:1024
	ds_read_b64_tr_b16 v[240:241], v151 offset:3072
	s_waitcnt lgkmcnt(9)
	v_mfma_f32_32x32x16_bf16 v[80:95], v[210:213], v[124:127], 0
	v_pk_add_f32 v[234:235], v[234:235], v[110:111]
	v_cvt_pk_bf16_f32 v182, v104, v105
	v_cvt_pk_bf16_f32 v184, v108, v109
	ds_read_b64_tr_b16 v[242:243], v151 offset:1536
	ds_read_b64_tr_b16 v[244:245], v151 offset:3584
	s_waitcnt lgkmcnt(10)
	v_mfma_f32_32x32x16_bf16 v[80:95], v[214:217], v[120:123], v[80:95]
	v_cvt_pk_bf16_f32 v183, v106, v107
	v_cvt_pk_bf16_f32 v185, v110, v111
	ds_read_b64_tr_b16 v[246:247], v151 offset:4096
	ds_read_b64_tr_b16 v[248:249], v151 offset:6144
	s_waitcnt lgkmcnt(11)
	v_mfma_f32_32x32x16_bf16 v[80:95], v[218:221], v[116:119], v[80:95]
	v_exp_f32_e32 v162, v162
	v_exp_f32_e32 v163, v163
	ds_read_b64_tr_b16 v[250:251], v151 offset:4608
	ds_read_b64_tr_b16 v[252:253], v151 offset:6656
	s_waitcnt lgkmcnt(12)
	v_mfma_f32_32x32x16_bf16 v[80:95], v[222:225], v[112:115], v[80:95]
	v_exp_f32_e32 v164, v164
	v_exp_f32_e32 v165, v165
	v_pk_add_f32 v[234:235], v[234:235], v[162:163]
	ds_read_b64_tr_b16 v[152:153], v151 offset:5120
	ds_read_b64_tr_b16 v[154:155], v151 offset:7168
	s_waitcnt lgkmcnt(12)
	v_mfma_f32_32x32x16_bf16 v[48:63], v[178:181], v[226:229], v[48:63]
	v_exp_f32_e32 v166, v166
	v_exp_f32_e32 v167, v167
	v_pk_add_f32 v[234:235], v[234:235], v[164:165]
	ds_read_b64_tr_b16 v[226:227], v151 offset:5632
	ds_read_b64_tr_b16 v[228:229], v151 offset:7680
	s_waitcnt lgkmcnt(12)
	v_mfma_f32_32x32x16_bf16 v[32:47], v[178:181], v[230:233], v[32:47]
	v_exp_f32_e32 v168, v168
	v_exp_f32_e32 v169, v169
	v_pk_add_f32 v[234:235], v[234:235], v[166:167]
	ds_read_b64_tr_b16 v[230:231], v151 offset:8192
	ds_read_b64_tr_b16 v[232:233], v151 offset:10240
	s_waitcnt lgkmcnt(12)
	v_mfma_f32_32x32x16_bf16 v[16:31], v[178:181], v[238:241], v[16:31]
	v_pk_add_f32 v[234:235], v[234:235], v[168:169]
	v_cvt_pk_bf16_f32 v186, v162, v163
	v_cvt_pk_bf16_f32 v188, v166, v167
	ds_read_b64_tr_b16 v[238:239], v151 offset:8704
	ds_read_b64_tr_b16 v[240:241], v151 offset:10752
	s_waitcnt lgkmcnt(12)
	v_mfma_f32_32x32x16_bf16 v[0:15], v[178:181], v[242:245], v[0:15]
	v_cvt_pk_bf16_f32 v187, v164, v165
	v_cvt_pk_bf16_f32 v189, v168, v169
	ds_read_b64_tr_b16 v[242:243], v151 offset:9216
	ds_read_b64_tr_b16 v[244:245], v151 offset:11264
	s_waitcnt lgkmcnt(12)
	v_mfma_f32_32x32x16_bf16 v[48:63], v[182:185], v[246:249], v[48:63]
	v_exp_f32_e32 v170, v170
	v_exp_f32_e32 v171, v171
	ds_read_b64_tr_b16 v[246:247], v151 offset:9728
	ds_read_b64_tr_b16 v[248:249], v151 offset:11776
	s_waitcnt lgkmcnt(12)
	v_mfma_f32_32x32x16_bf16 v[32:47], v[182:185], v[250:253], v[32:47]
	v_exp_f32_e32 v172, v172
	v_exp_f32_e32 v173, v173
	v_pk_add_f32 v[234:235], v[234:235], v[170:171]
	ds_read_b64_tr_b16 v[250:251], v151 offset:12288
	ds_read_b64_tr_b16 v[252:253], v151 offset:14336
	s_waitcnt lgkmcnt(12)
	v_mfma_f32_32x32x16_bf16 v[16:31], v[182:185], v[152:155], v[16:31]
	v_exp_f32_e32 v174, v174
	v_exp_f32_e32 v175, v175
	v_pk_add_f32 v[234:235], v[234:235], v[172:173]
	ds_read_b64_tr_b16 v[152:153], v151 offset:12800
	ds_read_b64_tr_b16 v[154:155], v151 offset:14848
	s_waitcnt lgkmcnt(12)
	v_mfma_f32_32x32x16_bf16 v[0:15], v[182:185], v[226:229], v[0:15]
	v_exp_f32_e32 v176, v176
	v_exp_f32_e32 v177, v177
	v_pk_add_f32 v[234:235], v[234:235], v[174:175]
	ds_read_b64_tr_b16 v[226:227], v151 offset:13312
	ds_read_b64_tr_b16 v[228:229], v151 offset:15360
	s_waitcnt lgkmcnt(12)
	v_mfma_f32_32x32x16_bf16 v[48:63], v[186:189], v[230:233], v[48:63]
	v_pk_add_f32 v[234:235], v[234:235], v[176:177]
	v_cvt_pk_bf16_f32 v190, v170, v171
	v_cvt_pk_bf16_f32 v192, v174, v175
	ds_read_b64_tr_b16 v[230:231], v151 offset:13824
	ds_read_b64_tr_b16 v[232:233], v151 offset:15872
	s_waitcnt lgkmcnt(12)
	v_mfma_f32_32x32x16_bf16 v[32:47], v[186:189], v[238:241], v[32:47]
	s_add_i32 s62, s62, 0x4000
	s_cmp_ge_u32 s62, 0x14000
	s_cselect_b32 s69, 0x14000, 0
	s_sub_i32 s62, s62, s69
	v_add_u32_e32 v151, s62, v140
	v_cvt_pk_bf16_f32 v191, v172, v173
	v_cvt_pk_bf16_f32 v193, v176, v177
	s_waitcnt lgkmcnt(10)
	v_mfma_f32_32x32x16_bf16 v[16:31], v[186:189], v[242:245], v[16:31]
	v_exp_f32_e32 v64, v64
	v_exp_f32_e32 v65, v65
	ds_read_b128 v[194:197], v149 offset:49152
	s_waitcnt lgkmcnt(9)
	v_mfma_f32_32x32x16_bf16 v[0:15], v[186:189], v[246:249], v[0:15]
	v_exp_f32_e32 v66, v66
	v_exp_f32_e32 v67, v67
	v_pk_add_f32 v[234:235], v[234:235], v[64:65]
	ds_read_b128 v[198:201], v148 offset:49152
	s_waitcnt lgkmcnt(8)
	v_mfma_f32_32x32x16_bf16 v[48:63], v[190:193], v[250:253], v[48:63]
	v_exp_f32_e32 v68, v68
	v_exp_f32_e32 v69, v69
	v_pk_add_f32 v[234:235], v[234:235], v[66:67]
	ds_read_b128 v[202:205], v143 offset:49152
	s_waitcnt lgkmcnt(7)
	v_mfma_f32_32x32x16_bf16 v[32:47], v[190:193], v[152:155], v[32:47]
	v_exp_f32_e32 v70, v70
	v_exp_f32_e32 v71, v71
	v_pk_add_f32 v[234:235], v[234:235], v[68:69]
	ds_read_b128 v[206:209], v141 offset:49152
	s_waitcnt lgkmcnt(6)
	v_mfma_f32_32x32x16_bf16 v[16:31], v[190:193], v[226:229], v[16:31]
	v_pk_add_f32 v[234:235], v[234:235], v[70:71]
	v_cvt_pk_bf16_f32 v178, v64, v65
	v_cvt_pk_bf16_f32 v180, v68, v69
	ds_read_b128 v[210:213], v149 offset:57344
	s_waitcnt lgkmcnt(5)
	v_mfma_f32_32x32x16_bf16 v[0:15], v[190:193], v[230:233], v[0:15]
	v_cvt_pk_bf16_f32 v179, v66, v67
	v_cvt_pk_bf16_f32 v181, v70, v71
	ds_read_b128 v[214:217], v148 offset:57344
	s_waitcnt lgkmcnt(5)
	v_mfma_f32_32x32x16_bf16 v[96:111], v[194:197], v[124:127], 0
	v_exp_f32_e32 v72, v72
	v_exp_f32_e32 v73, v73
	ds_read_b128 v[218:221], v143 offset:57344
	s_waitcnt lgkmcnt(5)
	v_mfma_f32_32x32x16_bf16 v[96:111], v[198:201], v[120:123], v[96:111]
	v_exp_f32_e32 v74, v74
	v_exp_f32_e32 v75, v75
	v_pk_add_f32 v[234:235], v[234:235], v[72:73]
	ds_read_b128 v[222:225], v141 offset:57344
	ds_read_b64_tr_b16 v[226:227], v151 offset:0
	ds_read_b64_tr_b16 v[228:229], v151 offset:2048
	s_waitcnt lgkmcnt(7)
	v_mfma_f32_32x32x16_bf16 v[96:111], v[202:205], v[116:119], v[96:111]
	v_exp_f32_e32 v76, v76
	v_exp_f32_e32 v77, v77
	v_pk_add_f32 v[234:235], v[234:235], v[74:75]
	ds_read_b64_tr_b16 v[230:231], v151 offset:512
	ds_read_b64_tr_b16 v[232:233], v151 offset:2560
	s_waitcnt lgkmcnt(8)
	v_mfma_f32_32x32x16_bf16 v[96:111], v[206:209], v[112:115], v[96:111]
	v_exp_f32_e32 v78, v78
	v_exp_f32_e32 v79, v79
	v_pk_add_f32 v[234:235], v[234:235], v[76:77]
	ds_read_b64_tr_b16 v[238:239], v151 offset:1024
	ds_read_b64_tr_b16 v[240:241], v151 offset:3072
	s_waitcnt lgkmcnt(9)
	v_mfma_f32_32x32x16_bf16 v[162:177], v[210:213], v[124:127], 0
	v_pk_add_f32 v[234:235], v[234:235], v[78:79]
	v_cvt_pk_bf16_f32 v182, v72, v73
	v_cvt_pk_bf16_f32 v184, v76, v77
	ds_read_b64_tr_b16 v[242:243], v151 offset:1536
	ds_read_b64_tr_b16 v[244:245], v151 offset:3584
	s_waitcnt lgkmcnt(10)
	v_mfma_f32_32x32x16_bf16 v[162:177], v[214:217], v[120:123], v[162:177]
	v_cvt_pk_bf16_f32 v183, v74, v75
	v_cvt_pk_bf16_f32 v185, v78, v79
	ds_read_b64_tr_b16 v[246:247], v151 offset:4096
	ds_read_b64_tr_b16 v[248:249], v151 offset:6144
	s_waitcnt lgkmcnt(11)
	v_mfma_f32_32x32x16_bf16 v[162:177], v[218:221], v[116:119], v[162:177]
	v_exp_f32_e32 v80, v80
	v_exp_f32_e32 v81, v81
	ds_read_b64_tr_b16 v[250:251], v151 offset:4608
	ds_read_b64_tr_b16 v[252:253], v151 offset:6656
	s_waitcnt lgkmcnt(12)
	v_mfma_f32_32x32x16_bf16 v[162:177], v[222:225], v[112:115], v[162:177]
	v_exp_f32_e32 v82, v82
	v_exp_f32_e32 v83, v83
	v_pk_add_f32 v[234:235], v[234:235], v[80:81]
	ds_read_b64_tr_b16 v[152:153], v151 offset:5120
	ds_read_b64_tr_b16 v[154:155], v151 offset:7168
	s_waitcnt lgkmcnt(12)
	v_mfma_f32_32x32x16_bf16 v[48:63], v[178:181], v[226:229], v[48:63]
	v_exp_f32_e32 v84, v84
	v_exp_f32_e32 v85, v85
	v_pk_add_f32 v[234:235], v[234:235], v[82:83]
	ds_read_b64_tr_b16 v[226:227], v151 offset:5632
	ds_read_b64_tr_b16 v[228:229], v151 offset:7680
	s_waitcnt lgkmcnt(12)
	v_mfma_f32_32x32x16_bf16 v[32:47], v[178:181], v[230:233], v[32:47]
	v_exp_f32_e32 v86, v86
	v_exp_f32_e32 v87, v87
	v_pk_add_f32 v[234:235], v[234:235], v[84:85]
	ds_read_b64_tr_b16 v[230:231], v151 offset:8192
	ds_read_b64_tr_b16 v[232:233], v151 offset:10240
	s_waitcnt lgkmcnt(12)
	v_mfma_f32_32x32x16_bf16 v[16:31], v[178:181], v[238:241], v[16:31]
	v_pk_add_f32 v[234:235], v[234:235], v[86:87]
	v_cvt_pk_bf16_f32 v186, v80, v81
	v_cvt_pk_bf16_f32 v188, v84, v85
	ds_read_b64_tr_b16 v[238:239], v151 offset:8704
	ds_read_b64_tr_b16 v[240:241], v151 offset:10752
	s_waitcnt lgkmcnt(12)
	v_mfma_f32_32x32x16_bf16 v[0:15], v[178:181], v[242:245], v[0:15]
	v_cvt_pk_bf16_f32 v187, v82, v83
	v_cvt_pk_bf16_f32 v189, v86, v87
	ds_read_b64_tr_b16 v[242:243], v151 offset:9216
	ds_read_b64_tr_b16 v[244:245], v151 offset:11264
	s_waitcnt lgkmcnt(12)
	v_mfma_f32_32x32x16_bf16 v[48:63], v[182:185], v[246:249], v[48:63]
	v_exp_f32_e32 v88, v88
	v_exp_f32_e32 v89, v89
	ds_read_b64_tr_b16 v[246:247], v151 offset:9728
	ds_read_b64_tr_b16 v[248:249], v151 offset:11776
	s_waitcnt lgkmcnt(12)
	v_mfma_f32_32x32x16_bf16 v[32:47], v[182:185], v[250:253], v[32:47]
	v_exp_f32_e32 v90, v90
	v_exp_f32_e32 v91, v91
	v_pk_add_f32 v[234:235], v[234:235], v[88:89]
	ds_read_b64_tr_b16 v[250:251], v151 offset:12288
	ds_read_b64_tr_b16 v[252:253], v151 offset:14336
	s_waitcnt lgkmcnt(12)
	v_mfma_f32_32x32x16_bf16 v[16:31], v[182:185], v[152:155], v[16:31]
	v_exp_f32_e32 v92, v92
	v_exp_f32_e32 v93, v93
	v_pk_add_f32 v[234:235], v[234:235], v[90:91]
	ds_read_b64_tr_b16 v[152:153], v151 offset:12800
	ds_read_b64_tr_b16 v[154:155], v151 offset:14848
	s_waitcnt lgkmcnt(12)
	v_mfma_f32_32x32x16_bf16 v[0:15], v[182:185], v[226:229], v[0:15]
	v_exp_f32_e32 v94, v94
	v_exp_f32_e32 v95, v95
	v_pk_add_f32 v[234:235], v[234:235], v[92:93]
	ds_read_b64_tr_b16 v[226:227], v151 offset:13312
	ds_read_b64_tr_b16 v[228:229], v151 offset:15360
	s_waitcnt lgkmcnt(12)
	v_mfma_f32_32x32x16_bf16 v[48:63], v[186:189], v[230:233], v[48:63]
	v_pk_add_f32 v[234:235], v[234:235], v[94:95]
	v_cvt_pk_bf16_f32 v190, v88, v89
	v_cvt_pk_bf16_f32 v192, v92, v93
	ds_read_b64_tr_b16 v[230:231], v151 offset:13824
	ds_read_b64_tr_b16 v[232:233], v151 offset:15872
	s_waitcnt lgkmcnt(12)
	v_mfma_f32_32x32x16_bf16 v[32:47], v[186:189], v[238:241], v[32:47]
	s_waitcnt vmcnt(0)
	s_barrier
	s_add_i32 s63, s62, 0xc000
	s_cmp_ge_u32 s63, 0x14000
	s_cselect_b32 s69, 0x14000, 0
	s_sub_i32 s63, s63, s69
	s_add_i32 s68, s62, 0x10000
	s_cmp_ge_u32 s68, 0x14000
	s_cselect_b32 s69, 0x14000, 0
	s_sub_i32 s68, s68, s69
	s_add_i32 s62, s62, 0x4000
	s_cmp_ge_u32 s62, 0x14000
	s_cselect_b32 s69, 0x14000, 0
	s_sub_i32 s62, s62, s69
	v_add_u32_e32 v151, s62, v140
	v_cvt_pk_bf16_f32 v191, v90, v91
	v_cvt_pk_bf16_f32 v193, v94, v95
	s_add_i32 m0, s41, s63
	s_add_u32 s42, s46, 0x5d81000
	s_addc_u32 s43, s47, 0
	global_load_lds_dwordx4 v150, s[42:43]
	s_waitcnt lgkmcnt(10)
	v_mfma_f32_32x32x16_bf16 v[16:31], v[186:189], v[242:245], v[16:31]
	v_exp_f32_e32 v96, v96
	v_exp_f32_e32 v97, v97
	ds_read_b128 v[194:197], v149 offset:0
	s_add_i32 m0, s71, s63
	s_add_u32 s42, s46, 0x5dc1000
	s_addc_u32 s43, s47, 0
	global_load_lds_dwordx4 v150, s[42:43]
	s_waitcnt lgkmcnt(9)
	v_mfma_f32_32x32x16_bf16 v[0:15], v[186:189], v[246:249], v[0:15]
	v_exp_f32_e32 v98, v98
	v_exp_f32_e32 v99, v99
	v_pk_add_f32 v[234:235], v[234:235], v[96:97]
	ds_read_b128 v[198:201], v148 offset:0
	s_add_i32 m0, s40, 0x8000
	s_add_u32 s42, s72, 0x5e00800
	s_addc_u32 s43, s73, 0
	global_load_lds_dwordx4 v142, s[42:43]
	s_waitcnt lgkmcnt(8)
	v_mfma_f32_32x32x16_bf16 v[48:63], v[190:193], v[250:253], v[48:63]
	v_exp_f32_e32 v100, v100
	v_exp_f32_e32 v101, v101
	v_pk_add_f32 v[234:235], v[234:235], v[98:99]
	ds_read_b128 v[202:205], v143 offset:0
	s_add_i32 m0, s40, 0xa000
	s_add_u32 s42, s72, 0x5e40800
	s_addc_u32 s43, s73, 0
	global_load_lds_dwordx4 v142, s[42:43]
	s_waitcnt lgkmcnt(7)
	v_mfma_f32_32x32x16_bf16 v[32:47], v[190:193], v[152:155], v[32:47]
	v_exp_f32_e32 v102, v102
	v_exp_f32_e32 v103, v103
	v_pk_add_f32 v[234:235], v[234:235], v[100:101]
	ds_read_b128 v[206:209], v141 offset:0
	s_add_i32 m0, s41, s68
	s_add_u32 s42, s46, 0x5e01000
	s_addc_u32 s43, s47, 0
	global_load_lds_dwordx4 v150, s[42:43]
	s_waitcnt lgkmcnt(6)
	v_mfma_f32_32x32x16_bf16 v[16:31], v[190:193], v[226:229], v[16:31]
	v_pk_add_f32 v[234:235], v[234:235], v[102:103]
	v_cvt_pk_bf16_f32 v178, v96, v97
	v_cvt_pk_bf16_f32 v180, v100, v101
	ds_read_b128 v[210:213], v149 offset:8192
	s_add_i32 m0, s71, s68
	s_add_u32 s42, s46, 0x5e41000
	s_addc_u32 s43, s47, 0
	global_load_lds_dwordx4 v150, s[42:43]
	s_waitcnt lgkmcnt(5)
	v_mfma_f32_32x32x16_bf16 v[0:15], v[190:193], v[230:233], v[0:15]
	v_cvt_pk_bf16_f32 v179, v98, v99
	v_cvt_pk_bf16_f32 v181, v102, v103
	ds_read_b128 v[214:217], v148 offset:8192
	s_add_i32 m0, s40, 0xc000
	s_add_u32 s42, s72, 0x5e80800
	s_addc_u32 s43, s73, 0
	global_load_lds_dwordx4 v142, s[42:43]
	s_add_i32 m0, s40, 0xe000
	s_add_u32 s42, s72, 0x5ec0800
	s_addc_u32 s43, s73, 0
	global_load_lds_dwordx4 v142, s[42:43]
	s_add_u32 s72, s72, 0x100000
	s_addc_u32 s73, s73, 0
	s_add_u32 s46, s46, 0x100000
	s_addc_u32 s47, s47, 0
	s_waitcnt lgkmcnt(5)
	v_mfma_f32_32x32x16_bf16 v[64:79], v[194:197], v[124:127], 0
	v_exp_f32_e32 v104, v104
	v_exp_f32_e32 v105, v105
	ds_read_b128 v[218:221], v143 offset:8192
	s_waitcnt lgkmcnt(5)
	v_mfma_f32_32x32x16_bf16 v[64:79], v[198:201], v[120:123], v[64:79]
	v_exp_f32_e32 v106, v106
	v_exp_f32_e32 v107, v107
	v_pk_add_f32 v[234:235], v[234:235], v[104:105]
	ds_read_b128 v[222:225], v141 offset:8192
	ds_read_b64_tr_b16 v[226:227], v151 offset:0
	ds_read_b64_tr_b16 v[228:229], v151 offset:2048
	s_waitcnt lgkmcnt(7)
	v_mfma_f32_32x32x16_bf16 v[64:79], v[202:205], v[116:119], v[64:79]
	v_exp_f32_e32 v108, v108
	v_exp_f32_e32 v109, v109
	v_pk_add_f32 v[234:235], v[234:235], v[106:107]
	ds_read_b64_tr_b16 v[230:231], v151 offset:512
	ds_read_b64_tr_b16 v[232:233], v151 offset:2560
	s_waitcnt lgkmcnt(8)
	v_mfma_f32_32x32x16_bf16 v[64:79], v[206:209], v[112:115], v[64:79]
	v_exp_f32_e32 v110, v110
	v_exp_f32_e32 v111, v111
	v_pk_add_f32 v[234:235], v[234:235], v[108:109]
	ds_read_b64_tr_b16 v[238:239], v151 offset:1024
	ds_read_b64_tr_b16 v[240:241], v151 offset:3072
	s_waitcnt lgkmcnt(9)
	v_mfma_f32_32x32x16_bf16 v[80:95], v[210:213], v[124:127], 0
	v_pk_add_f32 v[234:235], v[234:235], v[110:111]
	v_cvt_pk_bf16_f32 v182, v104, v105
	v_cvt_pk_bf16_f32 v184, v108, v109
	ds_read_b64_tr_b16 v[242:243], v151 offset:1536
	ds_read_b64_tr_b16 v[244:245], v151 offset:3584
	s_waitcnt lgkmcnt(10)
	v_mfma_f32_32x32x16_bf16 v[80:95], v[214:217], v[120:123], v[80:95]
	v_cvt_pk_bf16_f32 v183, v106, v107
	v_cvt_pk_bf16_f32 v185, v110, v111
	ds_read_b64_tr_b16 v[246:247], v151 offset:4096
	ds_read_b64_tr_b16 v[248:249], v151 offset:6144
	s_waitcnt lgkmcnt(11)
	v_mfma_f32_32x32x16_bf16 v[80:95], v[218:221], v[116:119], v[80:95]
	v_exp_f32_e32 v162, v162
	v_exp_f32_e32 v163, v163
	ds_read_b64_tr_b16 v[250:251], v151 offset:4608
	ds_read_b64_tr_b16 v[252:253], v151 offset:6656
	s_waitcnt lgkmcnt(12)
	v_mfma_f32_32x32x16_bf16 v[80:95], v[222:225], v[112:115], v[80:95]
	v_exp_f32_e32 v164, v164
	v_exp_f32_e32 v165, v165
	v_pk_add_f32 v[234:235], v[234:235], v[162:163]
	ds_read_b64_tr_b16 v[152:153], v151 offset:5120
	ds_read_b64_tr_b16 v[154:155], v151 offset:7168
	s_waitcnt lgkmcnt(12)
	v_mfma_f32_32x32x16_bf16 v[48:63], v[178:181], v[226:229], v[48:63]
	v_exp_f32_e32 v166, v166
	v_exp_f32_e32 v167, v167
	v_pk_add_f32 v[234:235], v[234:235], v[164:165]
	ds_read_b64_tr_b16 v[226:227], v151 offset:5632
	ds_read_b64_tr_b16 v[228:229], v151 offset:7680
	s_waitcnt lgkmcnt(12)
	v_mfma_f32_32x32x16_bf16 v[32:47], v[178:181], v[230:233], v[32:47]
	v_exp_f32_e32 v168, v168
	v_exp_f32_e32 v169, v169
	v_pk_add_f32 v[234:235], v[234:235], v[166:167]
	ds_read_b64_tr_b16 v[230:231], v151 offset:8192
	ds_read_b64_tr_b16 v[232:233], v151 offset:10240
	s_waitcnt lgkmcnt(12)
	v_mfma_f32_32x32x16_bf16 v[16:31], v[178:181], v[238:241], v[16:31]
	v_pk_add_f32 v[234:235], v[234:235], v[168:169]
	v_cvt_pk_bf16_f32 v186, v162, v163
	v_cvt_pk_bf16_f32 v188, v166, v167
	ds_read_b64_tr_b16 v[238:239], v151 offset:8704
	ds_read_b64_tr_b16 v[240:241], v151 offset:10752
	s_waitcnt lgkmcnt(12)
	v_mfma_f32_32x32x16_bf16 v[0:15], v[178:181], v[242:245], v[0:15]
	v_cvt_pk_bf16_f32 v187, v164, v165
	v_cvt_pk_bf16_f32 v189, v168, v169
	ds_read_b64_tr_b16 v[242:243], v151 offset:9216
	ds_read_b64_tr_b16 v[244:245], v151 offset:11264
	s_waitcnt lgkmcnt(12)
	v_mfma_f32_32x32x16_bf16 v[48:63], v[182:185], v[246:249], v[48:63]
	v_exp_f32_e32 v170, v170
	v_exp_f32_e32 v171, v171
	ds_read_b64_tr_b16 v[246:247], v151 offset:9728
	ds_read_b64_tr_b16 v[248:249], v151 offset:11776
	s_waitcnt lgkmcnt(12)
	v_mfma_f32_32x32x16_bf16 v[32:47], v[182:185], v[250:253], v[32:47]
	v_exp_f32_e32 v172, v172
	v_exp_f32_e32 v173, v173
	v_pk_add_f32 v[234:235], v[234:235], v[170:171]
	ds_read_b64_tr_b16 v[250:251], v151 offset:12288
	ds_read_b64_tr_b16 v[252:253], v151 offset:14336
	s_waitcnt lgkmcnt(12)
	v_mfma_f32_32x32x16_bf16 v[16:31], v[182:185], v[152:155], v[16:31]
	v_exp_f32_e32 v174, v174
	v_exp_f32_e32 v175, v175
	v_pk_add_f32 v[234:235], v[234:235], v[172:173]
	ds_read_b64_tr_b16 v[152:153], v151 offset:12800
	ds_read_b64_tr_b16 v[154:155], v151 offset:14848
	s_waitcnt lgkmcnt(12)
	v_mfma_f32_32x32x16_bf16 v[0:15], v[182:185], v[226:229], v[0:15]
	v_exp_f32_e32 v176, v176
	v_exp_f32_e32 v177, v177
	v_pk_add_f32 v[234:235], v[234:235], v[174:175]
	ds_read_b64_tr_b16 v[226:227], v151 offset:13312
	ds_read_b64_tr_b16 v[228:229], v151 offset:15360
	s_waitcnt lgkmcnt(12)
	v_mfma_f32_32x32x16_bf16 v[48:63], v[186:189], v[230:233], v[48:63]
	v_pk_add_f32 v[234:235], v[234:235], v[176:177]
	v_cvt_pk_bf16_f32 v190, v170, v171
	v_cvt_pk_bf16_f32 v192, v174, v175
	ds_read_b64_tr_b16 v[230:231], v151 offset:13824
	ds_read_b64_tr_b16 v[232:233], v151 offset:15872
	s_waitcnt lgkmcnt(12)
	v_mfma_f32_32x32x16_bf16 v[32:47], v[186:189], v[238:241], v[32:47]
	s_add_i32 s62, s62, 0x4000
	s_cmp_ge_u32 s62, 0x14000
	s_cselect_b32 s69, 0x14000, 0
	s_sub_i32 s62, s62, s69
	v_add_u32_e32 v151, s62, v140
	v_cvt_pk_bf16_f32 v191, v172, v173
	v_cvt_pk_bf16_f32 v193, v176, v177
	s_waitcnt lgkmcnt(10)
	v_mfma_f32_32x32x16_bf16 v[16:31], v[186:189], v[242:245], v[16:31]
	v_exp_f32_e32 v64, v64
	v_exp_f32_e32 v65, v65
	ds_read_b128 v[194:197], v149 offset:16384
	s_waitcnt lgkmcnt(9)
	v_mfma_f32_32x32x16_bf16 v[0:15], v[186:189], v[246:249], v[0:15]
	v_exp_f32_e32 v66, v66
	v_exp_f32_e32 v67, v67
	v_pk_add_f32 v[234:235], v[234:235], v[64:65]
	ds_read_b128 v[198:201], v148 offset:16384
	s_waitcnt lgkmcnt(8)
	v_mfma_f32_32x32x16_bf16 v[48:63], v[190:193], v[250:253], v[48:63]
	v_exp_f32_e32 v68, v68
	v_exp_f32_e32 v69, v69
	v_pk_add_f32 v[234:235], v[234:235], v[66:67]
	ds_read_b128 v[202:205], v143 offset:16384
	s_waitcnt lgkmcnt(7)
	v_mfma_f32_32x32x16_bf16 v[32:47], v[190:193], v[152:155], v[32:47]
	v_exp_f32_e32 v70, v70
	v_exp_f32_e32 v71, v71
	v_pk_add_f32 v[234:235], v[234:235], v[68:69]
	ds_read_b128 v[206:209], v141 offset:16384
	s_waitcnt lgkmcnt(6)
	v_mfma_f32_32x32x16_bf16 v[16:31], v[190:193], v[226:229], v[16:31]
	v_pk_add_f32 v[234:235], v[234:235], v[70:71]
	v_cvt_pk_bf16_f32 v178, v64, v65
	v_cvt_pk_bf16_f32 v180, v68, v69
	ds_read_b128 v[210:213], v149 offset:24576
	s_waitcnt lgkmcnt(5)
	v_mfma_f32_32x32x16_bf16 v[0:15], v[190:193], v[230:233], v[0:15]
	v_cvt_pk_bf16_f32 v179, v66, v67
	v_cvt_pk_bf16_f32 v181, v70, v71
	ds_read_b128 v[214:217], v148 offset:24576
	s_sub_i32 s70, s70, 1
	s_cmp_lg_u32 s70, 0
	s_cbranch_scc1 .Lda_loop
	s_waitcnt lgkmcnt(5)
	v_mfma_f32_32x32x16_bf16 v[96:111], v[194:197], v[124:127], 0
	v_exp_f32_e32 v72, v72
	v_exp_f32_e32 v73, v73
	ds_read_b128 v[218:221], v143 offset:24576
	s_waitcnt lgkmcnt(5)
	v_mfma_f32_32x32x16_bf16 v[96:111], v[198:201], v[120:123], v[96:111]
	v_exp_f32_e32 v74, v74
	v_exp_f32_e32 v75, v75
	v_pk_add_f32 v[234:235], v[234:235], v[72:73]
	ds_read_b128 v[222:225], v141 offset:24576
	ds_read_b64_tr_b16 v[226:227], v151 offset:0
	ds_read_b64_tr_b16 v[228:229], v151 offset:2048
	s_waitcnt lgkmcnt(7)
	v_mfma_f32_32x32x16_bf16 v[96:111], v[202:205], v[116:119], v[96:111]
	v_exp_f32_e32 v76, v76
	v_exp_f32_e32 v77, v77
	v_pk_add_f32 v[234:235], v[234:235], v[74:75]
	ds_read_b64_tr_b16 v[230:231], v151 offset:512
	ds_read_b64_tr_b16 v[232:233], v151 offset:2560
	s_waitcnt lgkmcnt(8)
	v_mfma_f32_32x32x16_bf16 v[96:111], v[206:209], v[112:115], v[96:111]
	v_exp_f32_e32 v78, v78
	v_exp_f32_e32 v79, v79
	v_pk_add_f32 v[234:235], v[234:235], v[76:77]
	ds_read_b64_tr_b16 v[238:239], v151 offset:1024
	ds_read_b64_tr_b16 v[240:241], v151 offset:3072
	s_waitcnt lgkmcnt(9)
	v_mfma_f32_32x32x16_bf16 v[162:177], v[210:213], v[124:127], 0
	v_pk_add_f32 v[234:235], v[234:235], v[78:79]
	v_cvt_pk_bf16_f32 v182, v72, v73
	v_cvt_pk_bf16_f32 v184, v76, v77
	ds_read_b64_tr_b16 v[242:243], v151 offset:1536
	ds_read_b64_tr_b16 v[244:245], v151 offset:3584
	s_waitcnt lgkmcnt(10)
	v_mfma_f32_32x32x16_bf16 v[162:177], v[214:217], v[120:123], v[162:177]
	v_cvt_pk_bf16_f32 v183, v74, v75
	v_cvt_pk_bf16_f32 v185, v78, v79
	ds_read_b64_tr_b16 v[246:247], v151 offset:4096
	ds_read_b64_tr_b16 v[248:249], v151 offset:6144
	s_waitcnt lgkmcnt(11)
	v_mfma_f32_32x32x16_bf16 v[162:177], v[218:221], v[116:119], v[162:177]
	v_exp_f32_e32 v80, v80
	v_exp_f32_e32 v81, v81
	ds_read_b64_tr_b16 v[250:251], v151 offset:4608
	ds_read_b64_tr_b16 v[252:253], v151 offset:6656
	s_waitcnt lgkmcnt(12)
	v_mfma_f32_32x32x16_bf16 v[162:177], v[222:225], v[112:115], v[162:177]
	v_exp_f32_e32 v82, v82
	v_exp_f32_e32 v83, v83
	v_pk_add_f32 v[234:235], v[234:235], v[80:81]
	ds_read_b64_tr_b16 v[152:153], v151 offset:5120
	ds_read_b64_tr_b16 v[154:155], v151 offset:7168
	s_waitcnt lgkmcnt(12)
	v_mfma_f32_32x32x16_bf16 v[48:63], v[178:181], v[226:229], v[48:63]
	v_exp_f32_e32 v84, v84
	v_exp_f32_e32 v85, v85
	v_pk_add_f32 v[234:235], v[234:235], v[82:83]
	ds_read_b64_tr_b16 v[226:227], v151 offset:5632
	ds_read_b64_tr_b16 v[228:229], v151 offset:7680
	s_waitcnt lgkmcnt(12)
	v_mfma_f32_32x32x16_bf16 v[32:47], v[178:181], v[230:233], v[32:47]
	v_exp_f32_e32 v86, v86
	v_exp_f32_e32 v87, v87
	v_pk_add_f32 v[234:235], v[234:235], v[84:85]
	ds_read_b64_tr_b16 v[230:231], v151 offset:8192
	ds_read_b64_tr_b16 v[232:233], v151 offset:10240
	s_waitcnt lgkmcnt(12)
	v_mfma_f32_32x32x16_bf16 v[16:31], v[178:181], v[238:241], v[16:31]
	v_pk_add_f32 v[234:235], v[234:235], v[86:87]
	v_cvt_pk_bf16_f32 v186, v80, v81
	v_cvt_pk_bf16_f32 v188, v84, v85
	ds_read_b64_tr_b16 v[238:239], v151 offset:8704
	ds_read_b64_tr_b16 v[240:241], v151 offset:10752
	s_waitcnt lgkmcnt(12)
	v_mfma_f32_32x32x16_bf16 v[0:15], v[178:181], v[242:245], v[0:15]
	v_cvt_pk_bf16_f32 v187, v82, v83
	v_cvt_pk_bf16_f32 v189, v86, v87
	ds_read_b64_tr_b16 v[242:243], v151 offset:9216
	ds_read_b64_tr_b16 v[244:245], v151 offset:11264
	s_waitcnt lgkmcnt(12)
	v_mfma_f32_32x32x16_bf16 v[48:63], v[182:185], v[246:249], v[48:63]
	v_exp_f32_e32 v88, v88
	v_exp_f32_e32 v89, v89
	ds_read_b64_tr_b16 v[246:247], v151 offset:9728
	ds_read_b64_tr_b16 v[248:249], v151 offset:11776
	s_waitcnt lgkmcnt(12)
	v_mfma_f32_32x32x16_bf16 v[32:47], v[182:185], v[250:253], v[32:47]
	v_exp_f32_e32 v90, v90
	v_exp_f32_e32 v91, v91
	v_pk_add_f32 v[234:235], v[234:235], v[88:89]
	ds_read_b64_tr_b16 v[250:251], v151 offset:12288
	ds_read_b64_tr_b16 v[252:253], v151 offset:14336
	s_waitcnt lgkmcnt(12)
	v_mfma_f32_32x32x16_bf16 v[16:31], v[182:185], v[152:155], v[16:31]
	v_exp_f32_e32 v92, v92
	v_exp_f32_e32 v93, v93
	v_pk_add_f32 v[234:235], v[234:235], v[90:91]
	ds_read_b64_tr_b16 v[152:153], v151 offset:12800
	ds_read_b64_tr_b16 v[154:155], v151 offset:14848
	s_waitcnt lgkmcnt(12)
	v_mfma_f32_32x32x16_bf16 v[0:15], v[182:185], v[226:229], v[0:15]
	v_exp_f32_e32 v94, v94
	v_exp_f32_e32 v95, v95
	v_pk_add_f32 v[234:235], v[234:235], v[92:93]
	ds_read_b64_tr_b16 v[226:227], v151 offset:13312
	ds_read_b64_tr_b16 v[228:229], v151 offset:15360
	s_waitcnt lgkmcnt(12)
	v_mfma_f32_32x32x16_bf16 v[48:63], v[186:189], v[230:233], v[48:63]
	v_pk_add_f32 v[234:235], v[234:235], v[94:95]
	v_cvt_pk_bf16_f32 v190, v88, v89
	v_cvt_pk_bf16_f32 v192, v92, v93
	ds_read_b64_tr_b16 v[230:231], v151 offset:13824
	ds_read_b64_tr_b16 v[232:233], v151 offset:15872
	s_waitcnt lgkmcnt(12)
	v_mfma_f32_32x32x16_bf16 v[32:47], v[186:189], v[238:241], v[32:47]
	s_waitcnt vmcnt(0)
	s_barrier
	s_add_i32 s63, s62, 0xc000
	s_cmp_ge_u32 s63, 0x14000
	s_cselect_b32 s69, 0x14000, 0
	s_sub_i32 s63, s63, s69
	s_add_i32 s62, s62, 0x4000
	s_cmp_ge_u32 s62, 0x14000
	s_cselect_b32 s69, 0x14000, 0
	s_sub_i32 s62, s62, s69
	v_add_u32_e32 v151, s62, v140
	v_cvt_pk_bf16_f32 v191, v90, v91
	v_cvt_pk_bf16_f32 v193, v94, v95
	s_add_i32 m0, s41, s63
	s_add_u32 s42, s46, 0x5d81000
	s_addc_u32 s43, s47, 0
	global_load_lds_dwordx4 v150, s[42:43]
	s_waitcnt lgkmcnt(10)
	v_mfma_f32_32x32x16_bf16 v[16:31], v[186:189], v[242:245], v[16:31]
	v_exp_f32_e32 v96, v96
	v_exp_f32_e32 v97, v97
	ds_read_b128 v[194:197], v149 offset:32768
	s_add_i32 m0, s71, s63
	s_add_u32 s42, s46, 0x5dc1000
	s_addc_u32 s43, s47, 0
	global_load_lds_dwordx4 v150, s[42:43]
	s_waitcnt lgkmcnt(9)
	v_mfma_f32_32x32x16_bf16 v[0:15], v[186:189], v[246:249], v[0:15]
	v_exp_f32_e32 v98, v98
	v_exp_f32_e32 v99, v99
	v_pk_add_f32 v[234:235], v[234:235], v[96:97]
	ds_read_b128 v[198:201], v148 offset:32768
	s_waitcnt lgkmcnt(8)
	v_mfma_f32_32x32x16_bf16 v[48:63], v[190:193], v[250:253], v[48:63]
	v_exp_f32_e32 v100, v100
	v_exp_f32_e32 v101, v101
	v_pk_add_f32 v[234:235], v[234:235], v[98:99]
	ds_read_b128 v[202:205], v143 offset:32768
	s_waitcnt lgkmcnt(7)
	v_mfma_f32_32x32x16_bf16 v[32:47], v[190:193], v[152:155], v[32:47]
	v_exp_f32_e32 v102, v102
	v_exp_f32_e32 v103, v103
	v_pk_add_f32 v[234:235], v[234:235], v[100:101]
	ds_read_b128 v[206:209], v141 offset:32768
	s_waitcnt lgkmcnt(6)
	v_mfma_f32_32x32x16_bf16 v[16:31], v[190:193], v[226:229], v[16:31]
	v_pk_add_f32 v[234:235], v[234:235], v[102:103]
	v_cvt_pk_bf16_f32 v178, v96, v97
	v_cvt_pk_bf16_f32 v180, v100, v101
	ds_read_b128 v[210:213], v149 offset:40960
	s_waitcnt lgkmcnt(5)
	v_mfma_f32_32x32x16_bf16 v[0:15], v[190:193], v[230:233], v[0:15]
	v_cvt_pk_bf16_f32 v179, v98, v99
	v_cvt_pk_bf16_f32 v181, v102, v103
	ds_read_b128 v[214:217], v148 offset:40960
	s_waitcnt lgkmcnt(5)
	v_mfma_f32_32x32x16_bf16 v[64:79], v[194:197], v[124:127], 0
	v_exp_f32_e32 v104, v104
	v_exp_f32_e32 v105, v105
	ds_read_b128 v[218:221], v143 offset:40960
	s_waitcnt lgkmcnt(5)
	v_mfma_f32_32x32x16_bf16 v[64:79], v[198:201], v[120:123], v[64:79]
	v_exp_f32_e32 v106, v106
	v_exp_f32_e32 v107, v107
	v_pk_add_f32 v[234:235], v[234:235], v[104:105]
	ds_read_b128 v[222:225], v141 offset:40960
	ds_read_b64_tr_b16 v[226:227], v151 offset:0
	ds_read_b64_tr_b16 v[228:229], v151 offset:2048
	s_waitcnt lgkmcnt(7)
	v_mfma_f32_32x32x16_bf16 v[64:79], v[202:205], v[116:119], v[64:79]
	v_exp_f32_e32 v108, v108
	v_exp_f32_e32 v109, v109
	v_pk_add_f32 v[234:235], v[234:235], v[106:107]
	ds_read_b64_tr_b16 v[230:231], v151 offset:512
	ds_read_b64_tr_b16 v[232:233], v151 offset:2560
	s_waitcnt lgkmcnt(8)
	v_mfma_f32_32x32x16_bf16 v[64:79], v[206:209], v[112:115], v[64:79]
	v_exp_f32_e32 v110, v110
	v_exp_f32_e32 v111, v111
	v_pk_add_f32 v[234:235], v[234:235], v[108:109]
	ds_read_b64_tr_b16 v[238:239], v151 offset:1024
	ds_read_b64_tr_b16 v[240:241], v151 offset:3072
	s_waitcnt lgkmcnt(9)
	v_mfma_f32_32x32x16_bf16 v[80:95], v[210:213], v[124:127], 0
	v_pk_add_f32 v[234:235], v[234:235], v[110:111]
	v_cvt_pk_bf16_f32 v182, v104, v105
	v_cvt_pk_bf16_f32 v184, v108, v109
	ds_read_b64_tr_b16 v[242:243], v151 offset:1536
	ds_read_b64_tr_b16 v[244:245], v151 offset:3584
	s_waitcnt lgkmcnt(10)
	v_mfma_f32_32x32x16_bf16 v[80:95], v[214:217], v[120:123], v[80:95]
	v_cvt_pk_bf16_f32 v183, v106, v107
	v_cvt_pk_bf16_f32 v185, v110, v111
	ds_read_b64_tr_b16 v[246:247], v151 offset:4096
	ds_read_b64_tr_b16 v[248:249], v151 offset:6144
	s_waitcnt lgkmcnt(11)
	v_mfma_f32_32x32x16_bf16 v[80:95], v[218:221], v[116:119], v[80:95]
	v_exp_f32_e32 v162, v162
	v_exp_f32_e32 v163, v163
	ds_read_b64_tr_b16 v[250:251], v151 offset:4608
	ds_read_b64_tr_b16 v[252:253], v151 offset:6656
	s_waitcnt lgkmcnt(12)
	v_mfma_f32_32x32x16_bf16 v[80:95], v[222:225], v[112:115], v[80:95]
	v_exp_f32_e32 v164, v164
	v_exp_f32_e32 v165, v165
	v_pk_add_f32 v[234:235], v[234:235], v[162:163]
	ds_read_b64_tr_b16 v[152:153], v151 offset:5120
	ds_read_b64_tr_b16 v[154:155], v151 offset:7168
	s_waitcnt lgkmcnt(12)
	v_mfma_f32_32x32x16_bf16 v[48:63], v[178:181], v[226:229], v[48:63]
	v_exp_f32_e32 v166, v166
	v_exp_f32_e32 v167, v167
	v_pk_add_f32 v[234:235], v[234:235], v[164:165]
	ds_read_b64_tr_b16 v[226:227], v151 offset:5632
	ds_read_b64_tr_b16 v[228:229], v151 offset:7680
	s_waitcnt lgkmcnt(12)
	v_mfma_f32_32x32x16_bf16 v[32:47], v[178:181], v[230:233], v[32:47]
	v_exp_f32_e32 v168, v168
	v_exp_f32_e32 v169, v169
	v_pk_add_f32 v[234:235], v[234:235], v[166:167]
	ds_read_b64_tr_b16 v[230:231], v151 offset:8192
	ds_read_b64_tr_b16 v[232:233], v151 offset:10240
	s_waitcnt lgkmcnt(12)
	v_mfma_f32_32x32x16_bf16 v[16:31], v[178:181], v[238:241], v[16:31]
	v_pk_add_f32 v[234:235], v[234:235], v[168:169]
	v_cvt_pk_bf16_f32 v186, v162, v163
	v_cvt_pk_bf16_f32 v188, v166, v167
	ds_read_b64_tr_b16 v[238:239], v151 offset:8704
	ds_read_b64_tr_b16 v[240:241], v151 offset:10752
	s_waitcnt lgkmcnt(12)
	v_mfma_f32_32x32x16_bf16 v[0:15], v[178:181], v[242:245], v[0:15]
	v_cvt_pk_bf16_f32 v187, v164, v165
	v_cvt_pk_bf16_f32 v189, v168, v169
	ds_read_b64_tr_b16 v[242:243], v151 offset:9216
	ds_read_b64_tr_b16 v[244:245], v151 offset:11264
	s_waitcnt lgkmcnt(12)
	v_mfma_f32_32x32x16_bf16 v[48:63], v[182:185], v[246:249], v[48:63]
	v_exp_f32_e32 v170, v170
	v_exp_f32_e32 v171, v171
	ds_read_b64_tr_b16 v[246:247], v151 offset:9728
	ds_read_b64_tr_b16 v[248:249], v151 offset:11776
	s_waitcnt lgkmcnt(12)
	v_mfma_f32_32x32x16_bf16 v[32:47], v[182:185], v[250:253], v[32:47]
	v_exp_f32_e32 v172, v172
	v_exp_f32_e32 v173, v173
	v_pk_add_f32 v[234:235], v[234:235], v[170:171]
	ds_read_b64_tr_b16 v[250:251], v151 offset:12288
	ds_read_b64_tr_b16 v[252:253], v151 offset:14336
	s_waitcnt lgkmcnt(12)
	v_mfma_f32_32x32x16_bf16 v[16:31], v[182:185], v[152:155], v[16:31]
	v_exp_f32_e32 v174, v174
	v_exp_f32_e32 v175, v175
	v_pk_add_f32 v[234:235], v[234:235], v[172:173]
	ds_read_b64_tr_b16 v[152:153], v151 offset:12800
	ds_read_b64_tr_b16 v[154:155], v151 offset:14848
	s_waitcnt lgkmcnt(12)
	v_mfma_f32_32x32x16_bf16 v[0:15], v[182:185], v[226:229], v[0:15]
	v_exp_f32_e32 v176, v176
	v_exp_f32_e32 v177, v177
	v_pk_add_f32 v[234:235], v[234:235], v[174:175]
	ds_read_b64_tr_b16 v[226:227], v151 offset:13312
	ds_read_b64_tr_b16 v[228:229], v151 offset:15360
	s_waitcnt lgkmcnt(12)
	v_mfma_f32_32x32x16_bf16 v[48:63], v[186:189], v[230:233], v[48:63]
	v_pk_add_f32 v[234:235], v[234:235], v[176:177]
	v_cvt_pk_bf16_f32 v190, v170, v171
	v_cvt_pk_bf16_f32 v192, v174, v175
	ds_read_b64_tr_b16 v[230:231], v151 offset:13824
	ds_read_b64_tr_b16 v[232:233], v151 offset:15872
	s_waitcnt lgkmcnt(12)
	v_mfma_f32_32x32x16_bf16 v[32:47], v[186:189], v[238:241], v[32:47]
	s_add_i32 s62, s62, 0x4000
	s_cmp_ge_u32 s62, 0x14000
	s_cselect_b32 s69, 0x14000, 0
	s_sub_i32 s62, s62, s69
	v_add_u32_e32 v151, s62, v140
	v_cvt_pk_bf16_f32 v191, v172, v173
	v_cvt_pk_bf16_f32 v193, v176, v177
	s_waitcnt lgkmcnt(10)
	v_mfma_f32_32x32x16_bf16 v[16:31], v[186:189], v[242:245], v[16:31]
	v_exp_f32_e32 v64, v64
	v_exp_f32_e32 v65, v65
	ds_read_b128 v[194:197], v149 offset:49152
	s_waitcnt lgkmcnt(9)
	v_mfma_f32_32x32x16_bf16 v[0:15], v[186:189], v[246:249], v[0:15]
	v_exp_f32_e32 v66, v66
	v_exp_f32_e32 v67, v67
	v_pk_add_f32 v[234:235], v[234:235], v[64:65]
	ds_read_b128 v[198:201], v148 offset:49152
	s_waitcnt lgkmcnt(8)
	v_mfma_f32_32x32x16_bf16 v[48:63], v[190:193], v[250:253], v[48:63]
	v_exp_f32_e32 v68, v68
	v_exp_f32_e32 v69, v69
	v_pk_add_f32 v[234:235], v[234:235], v[66:67]
	ds_read_b128 v[202:205], v143 offset:49152
	s_waitcnt lgkmcnt(7)
	v_mfma_f32_32x32x16_bf16 v[32:47], v[190:193], v[152:155], v[32:47]
	v_exp_f32_e32 v70, v70
	v_exp_f32_e32 v71, v71
	v_pk_add_f32 v[234:235], v[234:235], v[68:69]
	ds_read_b128 v[206:209], v141 offset:49152
	s_waitcnt lgkmcnt(6)
	v_mfma_f32_32x32x16_bf16 v[16:31], v[190:193], v[226:229], v[16:31]
	v_pk_add_f32 v[234:235], v[234:235], v[70:71]
	v_cvt_pk_bf16_f32 v178, v64, v65
	v_cvt_pk_bf16_f32 v180, v68, v69
	ds_read_b128 v[210:213], v149 offset:57344
	s_waitcnt lgkmcnt(5)
	v_mfma_f32_32x32x16_bf16 v[0:15], v[190:193], v[230:233], v[0:15]
	v_cvt_pk_bf16_f32 v179, v66, v67
	v_cvt_pk_bf16_f32 v181, v70, v71
	ds_read_b128 v[214:217], v148 offset:57344
	s_waitcnt lgkmcnt(5)
	v_mfma_f32_32x32x16_bf16 v[96:111], v[194:197], v[124:127], 0
	v_exp_f32_e32 v72, v72
	v_exp_f32_e32 v73, v73
	ds_read_b128 v[218:221], v143 offset:57344
	s_waitcnt lgkmcnt(5)
	v_mfma_f32_32x32x16_bf16 v[96:111], v[198:201], v[120:123], v[96:111]
	v_exp_f32_e32 v74, v74
	v_exp_f32_e32 v75, v75
	v_pk_add_f32 v[234:235], v[234:235], v[72:73]
	ds_read_b128 v[222:225], v141 offset:57344
	ds_read_b64_tr_b16 v[226:227], v151 offset:0
	ds_read_b64_tr_b16 v[228:229], v151 offset:2048
	s_waitcnt lgkmcnt(7)
	v_mfma_f32_32x32x16_bf16 v[96:111], v[202:205], v[116:119], v[96:111]
	v_exp_f32_e32 v76, v76
	v_exp_f32_e32 v77, v77
	v_pk_add_f32 v[234:235], v[234:235], v[74:75]
	ds_read_b64_tr_b16 v[230:231], v151 offset:512
	ds_read_b64_tr_b16 v[232:233], v151 offset:2560
	s_waitcnt lgkmcnt(8)
	v_mfma_f32_32x32x16_bf16 v[96:111], v[206:209], v[112:115], v[96:111]
	v_exp_f32_e32 v78, v78
	v_exp_f32_e32 v79, v79
	v_pk_add_f32 v[234:235], v[234:235], v[76:77]
	ds_read_b64_tr_b16 v[238:239], v151 offset:1024
	ds_read_b64_tr_b16 v[240:241], v151 offset:3072
	s_waitcnt lgkmcnt(9)
	v_mfma_f32_32x32x16_bf16 v[162:177], v[210:213], v[124:127], 0
	v_pk_add_f32 v[234:235], v[234:235], v[78:79]
	v_cvt_pk_bf16_f32 v182, v72, v73
	v_cvt_pk_bf16_f32 v184, v76, v77
	ds_read_b64_tr_b16 v[242:243], v151 offset:1536
	ds_read_b64_tr_b16 v[244:245], v151 offset:3584
	s_waitcnt lgkmcnt(10)
	v_mfma_f32_32x32x16_bf16 v[162:177], v[214:217], v[120:123], v[162:177]
	v_cvt_pk_bf16_f32 v183, v74, v75
	v_cvt_pk_bf16_f32 v185, v78, v79
	ds_read_b64_tr_b16 v[246:247], v151 offset:4096
	ds_read_b64_tr_b16 v[248:249], v151 offset:6144
	s_waitcnt lgkmcnt(11)
	v_mfma_f32_32x32x16_bf16 v[162:177], v[218:221], v[116:119], v[162:177]
	v_exp_f32_e32 v80, v80
	v_exp_f32_e32 v81, v81
	ds_read_b64_tr_b16 v[250:251], v151 offset:4608
	ds_read_b64_tr_b16 v[252:253], v151 offset:6656
	s_waitcnt lgkmcnt(12)
	v_mfma_f32_32x32x16_bf16 v[162:177], v[222:225], v[112:115], v[162:177]
	v_exp_f32_e32 v82, v82
	v_exp_f32_e32 v83, v83
	v_pk_add_f32 v[234:235], v[234:235], v[80:81]
	ds_read_b64_tr_b16 v[152:153], v151 offset:5120
	ds_read_b64_tr_b16 v[154:155], v151 offset:7168
	s_waitcnt lgkmcnt(12)
	v_mfma_f32_32x32x16_bf16 v[48:63], v[178:181], v[226:229], v[48:63]
	v_exp_f32_e32 v84, v84
	v_exp_f32_e32 v85, v85
	v_pk_add_f32 v[234:235], v[234:235], v[82:83]
	ds_read_b64_tr_b16 v[226:227], v151 offset:5632
	ds_read_b64_tr_b16 v[228:229], v151 offset:7680
	s_waitcnt lgkmcnt(12)
	v_mfma_f32_32x32x16_bf16 v[32:47], v[178:181], v[230:233], v[32:47]
	v_exp_f32_e32 v86, v86
	v_exp_f32_e32 v87, v87
	v_pk_add_f32 v[234:235], v[234:235], v[84:85]
	ds_read_b64_tr_b16 v[230:231], v151 offset:8192
	ds_read_b64_tr_b16 v[232:233], v151 offset:10240
	s_waitcnt lgkmcnt(12)
	v_mfma_f32_32x32x16_bf16 v[16:31], v[178:181], v[238:241], v[16:31]
	v_pk_add_f32 v[234:235], v[234:235], v[86:87]
	v_cvt_pk_bf16_f32 v186, v80, v81
	v_cvt_pk_bf16_f32 v188, v84, v85
	ds_read_b64_tr_b16 v[238:239], v151 offset:8704
	ds_read_b64_tr_b16 v[240:241], v151 offset:10752
	s_waitcnt lgkmcnt(12)
	v_mfma_f32_32x32x16_bf16 v[0:15], v[178:181], v[242:245], v[0:15]
	v_cvt_pk_bf16_f32 v187, v82, v83
	v_cvt_pk_bf16_f32 v189, v86, v87
	ds_read_b64_tr_b16 v[242:243], v151 offset:9216
	ds_read_b64_tr_b16 v[244:245], v151 offset:11264
	s_waitcnt lgkmcnt(12)
	v_mfma_f32_32x32x16_bf16 v[48:63], v[182:185], v[246:249], v[48:63]
	v_exp_f32_e32 v88, v88
	v_exp_f32_e32 v89, v89
	ds_read_b64_tr_b16 v[246:247], v151 offset:9728
	ds_read_b64_tr_b16 v[248:249], v151 offset:11776
	s_waitcnt lgkmcnt(12)
	v_mfma_f32_32x32x16_bf16 v[32:47], v[182:185], v[250:253], v[32:47]
	v_exp_f32_e32 v90, v90
	v_exp_f32_e32 v91, v91
	v_pk_add_f32 v[234:235], v[234:235], v[88:89]
	ds_read_b64_tr_b16 v[250:251], v151 offset:12288
	ds_read_b64_tr_b16 v[252:253], v151 offset:14336
	s_waitcnt lgkmcnt(12)
	v_mfma_f32_32x32x16_bf16 v[16:31], v[182:185], v[152:155], v[16:31]
	v_exp_f32_e32 v92, v92
	v_exp_f32_e32 v93, v93
	v_pk_add_f32 v[234:235], v[234:235], v[90:91]
	ds_read_b64_tr_b16 v[152:153], v151 offset:12800
	ds_read_b64_tr_b16 v[154:155], v151 offset:14848
	s_waitcnt lgkmcnt(12)
	v_mfma_f32_32x32x16_bf16 v[0:15], v[182:185], v[226:229], v[0:15]
	v_exp_f32_e32 v94, v94
	v_exp_f32_e32 v95, v95
	v_pk_add_f32 v[234:235], v[234:235], v[92:93]
	ds_read_b64_tr_b16 v[226:227], v151 offset:13312
	ds_read_b64_tr_b16 v[228:229], v151 offset:15360
	s_waitcnt lgkmcnt(12)
	v_mfma_f32_32x32x16_bf16 v[48:63], v[186:189], v[230:233], v[48:63]
	v_pk_add_f32 v[234:235], v[234:235], v[94:95]
	v_cvt_pk_bf16_f32 v190, v88, v89
	v_cvt_pk_bf16_f32 v192, v92, v93
	ds_read_b64_tr_b16 v[230:231], v151 offset:13824
	ds_read_b64_tr_b16 v[232:233], v151 offset:15872
	s_waitcnt lgkmcnt(12)
	v_mfma_f32_32x32x16_bf16 v[32:47], v[186:189], v[238:241], v[32:47]
	s_waitcnt vmcnt(0)
	s_barrier
	s_add_i32 s62, s62, 0x4000
	s_cmp_ge_u32 s62, 0x14000
	s_cselect_b32 s69, 0x14000, 0
	s_sub_i32 s62, s62, s69
	v_add_u32_e32 v151, s62, v140
	v_cvt_pk_bf16_f32 v191, v90, v91
	v_cvt_pk_bf16_f32 v193, v94, v95
	s_waitcnt lgkmcnt(10)
	v_mfma_f32_32x32x16_bf16 v[16:31], v[186:189], v[242:245], v[16:31]
	v_exp_f32_e32 v96, v96
	v_exp_f32_e32 v97, v97
	s_waitcnt lgkmcnt(8)
	v_mfma_f32_32x32x16_bf16 v[0:15], v[186:189], v[246:249], v[0:15]
	v_exp_f32_e32 v98, v98
	v_exp_f32_e32 v99, v99
	v_pk_add_f32 v[234:235], v[234:235], v[96:97]
	s_waitcnt lgkmcnt(6)
	v_mfma_f32_32x32x16_bf16 v[48:63], v[190:193], v[250:253], v[48:63]
	v_exp_f32_e32 v100, v100
	v_exp_f32_e32 v101, v101
	v_pk_add_f32 v[234:235], v[234:235], v[98:99]
	s_waitcnt lgkmcnt(4)
	v_mfma_f32_32x32x16_bf16 v[32:47], v[190:193], v[152:155], v[32:47]
	v_exp_f32_e32 v102, v102
	v_exp_f32_e32 v103, v103
	v_pk_add_f32 v[234:235], v[234:235], v[100:101]
	s_waitcnt lgkmcnt(2)
	v_mfma_f32_32x32x16_bf16 v[16:31], v[190:193], v[226:229], v[16:31]
	v_pk_add_f32 v[234:235], v[234:235], v[102:103]
	v_cvt_pk_bf16_f32 v178, v96, v97
	v_cvt_pk_bf16_f32 v180, v100, v101
	s_waitcnt lgkmcnt(0)
	v_mfma_f32_32x32x16_bf16 v[0:15], v[190:193], v[230:233], v[0:15]
	v_cvt_pk_bf16_f32 v179, v98, v99
	v_cvt_pk_bf16_f32 v181, v102, v103
	v_exp_f32_e32 v104, v104
	v_exp_f32_e32 v105, v105
	v_exp_f32_e32 v106, v106
	v_exp_f32_e32 v107, v107
	v_pk_add_f32 v[234:235], v[234:235], v[104:105]
	ds_read_b64_tr_b16 v[226:227], v151 offset:0
	ds_read_b64_tr_b16 v[228:229], v151 offset:2048
	v_exp_f32_e32 v108, v108
	v_exp_f32_e32 v109, v109
	v_pk_add_f32 v[234:235], v[234:235], v[106:107]
	ds_read_b64_tr_b16 v[230:231], v151 offset:512
	ds_read_b64_tr_b16 v[232:233], v151 offset:2560
	v_exp_f32_e32 v110, v110
	v_exp_f32_e32 v111, v111
	v_pk_add_f32 v[234:235], v[234:235], v[108:109]
	ds_read_b64_tr_b16 v[238:239], v151 offset:1024
	ds_read_b64_tr_b16 v[240:241], v151 offset:3072
	v_pk_add_f32 v[234:235], v[234:235], v[110:111]
	v_cvt_pk_bf16_f32 v182, v104, v105
	v_cvt_pk_bf16_f32 v184, v108, v109
	ds_read_b64_tr_b16 v[242:243], v151 offset:1536
	ds_read_b64_tr_b16 v[244:245], v151 offset:3584
	v_cvt_pk_bf16_f32 v183, v106, v107
	v_cvt_pk_bf16_f32 v185, v110, v111
	ds_read_b64_tr_b16 v[246:247], v151 offset:4096
	ds_read_b64_tr_b16 v[248:249], v151 offset:6144
	v_exp_f32_e32 v162, v162
	v_exp_f32_e32 v163, v163
	ds_read_b64_tr_b16 v[250:251], v151 offset:4608
	ds_read_b64_tr_b16 v[252:253], v151 offset:6656
	v_exp_f32_e32 v164, v164
	v_exp_f32_e32 v165, v165
	v_pk_add_f32 v[234:235], v[234:235], v[162:163]
	ds_read_b64_tr_b16 v[152:153], v151 offset:5120
	ds_read_b64_tr_b16 v[154:155], v151 offset:7168
	s_waitcnt lgkmcnt(12)
	v_mfma_f32_32x32x16_bf16 v[48:63], v[178:181], v[226:229], v[48:63]
	v_exp_f32_e32 v166, v166
	v_exp_f32_e32 v167, v167
	v_pk_add_f32 v[234:235], v[234:235], v[164:165]
	ds_read_b64_tr_b16 v[226:227], v151 offset:5632
	ds_read_b64_tr_b16 v[228:229], v151 offset:7680
	s_waitcnt lgkmcnt(12)
	v_mfma_f32_32x32x16_bf16 v[32:47], v[178:181], v[230:233], v[32:47]
	v_exp_f32_e32 v168, v168
	v_exp_f32_e32 v169, v169
	v_pk_add_f32 v[234:235], v[234:235], v[166:167]
	ds_read_b64_tr_b16 v[230:231], v151 offset:8192
	ds_read_b64_tr_b16 v[232:233], v151 offset:10240
	s_waitcnt lgkmcnt(12)
	v_mfma_f32_32x32x16_bf16 v[16:31], v[178:181], v[238:241], v[16:31]
	v_pk_add_f32 v[234:235], v[234:235], v[168:169]
	v_cvt_pk_bf16_f32 v186, v162, v163
	v_cvt_pk_bf16_f32 v188, v166, v167
	ds_read_b64_tr_b16 v[238:239], v151 offset:8704
	ds_read_b64_tr_b16 v[240:241], v151 offset:10752
	s_waitcnt lgkmcnt(12)
	v_mfma_f32_32x32x16_bf16 v[0:15], v[178:181], v[242:245], v[0:15]
	v_cvt_pk_bf16_f32 v187, v164, v165
	v_cvt_pk_bf16_f32 v189, v168, v169
	ds_read_b64_tr_b16 v[242:243], v151 offset:9216
	ds_read_b64_tr_b16 v[244:245], v151 offset:11264
	s_waitcnt lgkmcnt(12)
	v_mfma_f32_32x32x16_bf16 v[48:63], v[182:185], v[246:249], v[48:63]
	v_exp_f32_e32 v170, v170
	v_exp_f32_e32 v171, v171
	ds_read_b64_tr_b16 v[246:247], v151 offset:9728
	ds_read_b64_tr_b16 v[248:249], v151 offset:11776
	s_waitcnt lgkmcnt(12)
	v_mfma_f32_32x32x16_bf16 v[32:47], v[182:185], v[250:253], v[32:47]
	v_exp_f32_e32 v172, v172
	v_exp_f32_e32 v173, v173
	v_pk_add_f32 v[234:235], v[234:235], v[170:171]
	ds_read_b64_tr_b16 v[250:251], v151 offset:12288
	ds_read_b64_tr_b16 v[252:253], v151 offset:14336
	s_waitcnt lgkmcnt(12)
	v_mfma_f32_32x32x16_bf16 v[16:31], v[182:185], v[152:155], v[16:31]
	v_exp_f32_e32 v174, v174
	v_exp_f32_e32 v175, v175
	v_pk_add_f32 v[234:235], v[234:235], v[172:173]
	ds_read_b64_tr_b16 v[152:153], v151 offset:12800
	ds_read_b64_tr_b16 v[154:155], v151 offset:14848
	s_waitcnt lgkmcnt(12)
	v_mfma_f32_32x32x16_bf16 v[0:15], v[182:185], v[226:229], v[0:15]
	v_exp_f32_e32 v176, v176
	v_exp_f32_e32 v177, v177
	v_pk_add_f32 v[234:235], v[234:235], v[174:175]
	ds_read_b64_tr_b16 v[226:227], v151 offset:13312
	ds_read_b64_tr_b16 v[228:229], v151 offset:15360
	s_waitcnt lgkmcnt(12)
	v_mfma_f32_32x32x16_bf16 v[48:63], v[186:189], v[230:233], v[48:63]
	v_pk_add_f32 v[234:235], v[234:235], v[176:177]
	v_cvt_pk_bf16_f32 v190, v170, v171
	v_cvt_pk_bf16_f32 v192, v174, v175
	ds_read_b64_tr_b16 v[230:231], v151 offset:13824
	ds_read_b64_tr_b16 v[232:233], v151 offset:15872
	s_waitcnt lgkmcnt(12)
	v_mfma_f32_32x32x16_bf16 v[32:47], v[186:189], v[238:241], v[32:47]
	s_add_i32 s62, s62, 0x4000
	s_cmp_ge_u32 s62, 0x14000
	s_cselect_b32 s69, 0x14000, 0
	s_sub_i32 s62, s62, s69
	v_add_u32_e32 v151, s62, v140
	v_cvt_pk_bf16_f32 v191, v172, v173
	v_cvt_pk_bf16_f32 v193, v176, v177
	s_waitcnt lgkmcnt(10)
	v_mfma_f32_32x32x16_bf16 v[16:31], v[186:189], v[242:245], v[16:31]
	s_waitcnt lgkmcnt(8)
	v_mfma_f32_32x32x16_bf16 v[0:15], v[186:189], v[246:249], v[0:15]
	s_waitcnt lgkmcnt(6)
	v_mfma_f32_32x32x16_bf16 v[48:63], v[190:193], v[250:253], v[48:63]
	s_waitcnt lgkmcnt(4)
	v_mfma_f32_32x32x16_bf16 v[32:47], v[190:193], v[152:155], v[32:47]
	s_waitcnt lgkmcnt(2)
	v_mfma_f32_32x32x16_bf16 v[16:31], v[190:193], v[226:229], v[16:31]
	s_waitcnt lgkmcnt(0)
	v_mfma_f32_32x32x16_bf16 v[0:15], v[190:193], v[230:233], v[0:15]
	v_add_f32_e32 v68, v234, v235
	v_mov_b32_e32 v69, 0
	v_mov_b32_e32 v71, 0
	v_mov_b32_e32 v70, v68
	v_mov_b32_e32 v128, 0
	s_nop 0
	v_permlane32_swap_b32_e32 v68, v70
	s_and_b32 s4, s35, 0x3fffffc0
	s_lshl_b32 s4, s4, 2
	s_add_i32 s7, s4, 0
	s_add_i32 s7, s7, 0x24000
	s_setprio 0
	v_add_f32_e32 v64, v68, v70
	v_lshl_add_u32 v66, v136, 2, s7
	ds_write_b32 v66, v64
	global_load_dword v116, v129, s[14:15]
	v_lshlrev_b32_e32 v117, 2, v136
	global_load_dword v112, v117, s[58:59] offset:0
	global_load_dword v113, v117, s[58:59] offset:128
	global_load_dword v114, v117, s[58:59] offset:256
	global_load_dword v115, v117, s[58:59] offset:384
	s_lshl_b32 s4, s19, 4
	s_add_i32 s4, s18, s4
	s_lshl_b32 s5, s4, 13
	s_add_u32 s42, s65, s6
	s_addc_u32 s43, s20, 0
	s_add_u32 s42, s42, s5
	s_addc_u32 s43, s43, 0
	s_lshl_b32 s5, s4, 11
	s_add_u32 s46, s21, s6
	s_addc_u32 s47, s22, 0
	s_add_u32 s46, s46, s5
	s_addc_u32 s47, s47, 0
	v_lshlrev_b32_e32 v118, 1, v136
	v_lshl_add_u32 v119, v137, 13, v118
	v_lshl_add_u32 v118, v137, 15, v118
	global_load_ushort v162, v118, s[42:43] offset:0
	global_load_ushort v163, v118, s[42:43] offset:64
	global_load_ushort v164, v118, s[42:43] offset:128
	global_load_ushort v165, v118, s[42:43] offset:192
	s_add_u32 s42, s42, 0x2000
	s_addc_u32 s43, s43, 0
	global_load_ushort v166, v118, s[42:43] offset:0
	global_load_ushort v167, v118, s[42:43] offset:64
	global_load_ushort v168, v118, s[42:43] offset:128
	global_load_ushort v169, v118, s[42:43] offset:192
	s_add_u32 s42, s42, 0x2000
	s_addc_u32 s43, s43, 0
	global_load_ushort v170, v118, s[42:43] offset:0
	global_load_ushort v171, v118, s[42:43] offset:64
	global_load_ushort v172, v118, s[42:43] offset:128
	global_load_ushort v173, v118, s[42:43] offset:192
	s_add_u32 s42, s42, 0x2000
	s_addc_u32 s43, s43, 0
	global_load_ushort v174, v118, s[42:43] offset:0
	global_load_ushort v175, v118, s[42:43] offset:64
	global_load_ushort v176, v118, s[42:43] offset:128
	global_load_ushort v177, v118, s[42:43] offset:192
	s_add_u32 s42, s42, 0xa000
	s_addc_u32 s43, s43, 0
	global_load_ushort v178, v118, s[42:43] offset:0
	global_load_ushort v179, v118, s[42:43] offset:64
	global_load_ushort v180, v118, s[42:43] offset:128
	global_load_ushort v181, v118, s[42:43] offset:192
	s_add_u32 s42, s42, 0x2000
	s_addc_u32 s43, s43, 0
	global_load_ushort v182, v118, s[42:43] offset:0
	global_load_ushort v183, v118, s[42:43] offset:64
	global_load_ushort v184, v118, s[42:43] offset:128
	global_load_ushort v185, v118, s[42:43] offset:192
	s_add_u32 s42, s42, 0x2000
	s_addc_u32 s43, s43, 0
	global_load_ushort v186, v118, s[42:43] offset:0
	global_load_ushort v187, v118, s[42:43] offset:64
	global_load_ushort v188, v118, s[42:43] offset:128
	global_load_ushort v189, v118, s[42:43] offset:192
	s_add_u32 s42, s42, 0x2000
	s_addc_u32 s43, s43, 0
	global_load_ushort v190, v118, s[42:43] offset:0
	global_load_ushort v191, v118, s[42:43] offset:64
	global_load_ushort v192, v118, s[42:43] offset:128
	global_load_ushort v193, v118, s[42:43] offset:192
	v_add_u32_e32 v65, s7, v130
	s_waitcnt lgkmcnt(0)
	ds_read_b128 v[80:83], v65
	ds_read_b128 v[84:87], v65 offset:32
	ds_read_b128 v[88:91], v65 offset:64
	ds_read_b128 v[92:95], v65 offset:96
	s_waitcnt lgkmcnt(0)
	v_rcp_f32_e32 v96, v80
	v_rcp_f32_e32 v97, v81
	v_rcp_f32_e32 v98, v82
	v_rcp_f32_e32 v99, v83
	v_rcp_f32_e32 v100, v84
	v_rcp_f32_e32 v101, v85
	v_rcp_f32_e32 v102, v86
	v_rcp_f32_e32 v103, v87
	v_rcp_f32_e32 v104, v88
	v_rcp_f32_e32 v105, v89
	v_rcp_f32_e32 v106, v90
	v_rcp_f32_e32 v107, v91
	v_rcp_f32_e32 v108, v92
	v_rcp_f32_e32 v109, v93
	v_rcp_f32_e32 v110, v94
	v_rcp_f32_e32 v111, v95
	s_waitcnt vmcnt(36)
	v_readfirstlane_b32 s5, v116
	s_nop 3
	s_cmp_eq_u32 s19, 0
	s_cselect_b32 s5, 1.0, s5
	s_cselect_b32 s10, 1.0, -1.0
	s_cselect_b32 s40, 0, 0x2000
	s_cselect_b32 s41, 0x2000, 0
	v_mul_f32_e32 v96, s5, v96
	v_mul_f32_e32 v97, s5, v97
	v_mul_f32_e32 v98, s5, v98
	v_mul_f32_e32 v99, s5, v99
	v_mul_f32_e32 v100, s5, v100
	v_mul_f32_e32 v101, s5, v101
	v_mul_f32_e32 v102, s5, v102
	v_mul_f32_e32 v103, s5, v103
	v_mul_f32_e32 v104, s5, v104
	v_mul_f32_e32 v105, s5, v105
	v_mul_f32_e32 v106, s5, v106
	v_mul_f32_e32 v107, s5, v107
	v_mul_f32_e32 v108, s5, v108
	v_mul_f32_e32 v109, s5, v109
	v_mul_f32_e32 v110, s5, v110
	v_mul_f32_e32 v111, s5, v111
	s_waitcnt vmcnt(32)
	v_mov_b32_e32 v120, 0x3f4ccccd
	v_mul_f32_e32 v120, s10, v120
	v_mul_f32_e32 v112, v120, v112
	v_mul_f32_e32 v113, v120, v113
	v_mul_f32_e32 v114, v120, v114
	v_mul_f32_e32 v115, v120, v115
	s_barrier
	s_lshl_b32 s11, s34, 14
	v_lshl_add_u32 v121, v137, 11, v117
	v_add_u32_e32 v121, s11, v121
	s_add_i32 s62, s40, 0x0
	v_add_u32_e32 v140, s62, v121
	s_add_i32 s62, s41, 0x0
	v_add_u32_e32 v122, s62, v121
	s_add_i32 s62, s40, 0x400
	v_add_u32_e32 v141, s62, v121
	s_add_i32 s62, s41, 0x400
	v_add_u32_e32 v123, s62, v121
	s_add_i32 s62, s40, 0x1000
	v_add_u32_e32 v142, s62, v121
	s_add_i32 s62, s41, 0x1000
	v_add_u32_e32 v124, s62, v121
	s_add_i32 s62, s40, 0x1400
	v_add_u32_e32 v143, s62, v121
	s_add_i32 s62, s41, 0x1400
	v_add_u32_e32 v125, s62, v121
	s_cmp_eq_u32 s19, 0
	s_cbranch_scc0 .Lde_c1
	v_mul_f32_e32 v194, v48, v96
	v_mul_f32_e32 v202, v32, v96
	v_mul_f32_e32 v210, v16, v96
	v_mul_f32_e32 v218, v0, v96
	v_mul_f32_e32 v195, v49, v97
	v_mul_f32_e32 v203, v33, v97
	v_mul_f32_e32 v211, v17, v97
	v_mul_f32_e32 v219, v1, v97
	v_mul_f32_e32 v196, v50, v98
	v_mul_f32_e32 v204, v34, v98
	v_mul_f32_e32 v212, v18, v98
	v_mul_f32_e32 v220, v2, v98
	v_mul_f32_e32 v197, v51, v99
	v_mul_f32_e32 v205, v35, v99
	v_mul_f32_e32 v213, v19, v99
	v_mul_f32_e32 v221, v3, v99
	v_mul_f32_e32 v198, v52, v100
	v_mul_f32_e32 v206, v36, v100
	v_mul_f32_e32 v214, v20, v100
	v_mul_f32_e32 v222, v4, v100
	v_mul_f32_e32 v199, v53, v101
	v_mul_f32_e32 v207, v37, v101
	v_mul_f32_e32 v215, v21, v101
	v_mul_f32_e32 v223, v5, v101
	v_mul_f32_e32 v200, v54, v102
	v_mul_f32_e32 v208, v38, v102
	v_mul_f32_e32 v216, v22, v102
	v_mul_f32_e32 v224, v6, v102
	v_mul_f32_e32 v201, v55, v103
	v_mul_f32_e32 v209, v39, v103
	v_mul_f32_e32 v217, v23, v103
	v_mul_f32_e32 v225, v7, v103
	v_mul_f32_e32 v226, v56, v104
	v_mul_f32_e32 v227, v40, v104
	ds_write2_b32 v122, v226, v227 offset0:0 offset1:32
	v_mul_f32_e32 v228, v24, v104
	v_mul_f32_e32 v229, v8, v104
	ds_write2_b32 v122, v228, v229 offset0:64 offset1:96
	v_mul_f32_e32 v230, v57, v105
	v_mul_f32_e32 v231, v41, v105
	ds_write2_b32 v122, v230, v231 offset0:128 offset1:160
	v_mul_f32_e32 v232, v25, v105
	v_mul_f32_e32 v233, v9, v105
	ds_write2_b32 v122, v232, v233 offset0:192 offset1:224
	v_mul_f32_e32 v238, v58, v106
	v_mul_f32_e32 v239, v42, v106
	ds_write2_b32 v123, v238, v239 offset0:0 offset1:32
	v_mul_f32_e32 v240, v26, v106
	v_mul_f32_e32 v241, v10, v106
	ds_write2_b32 v123, v240, v241 offset0:64 offset1:96
	v_mul_f32_e32 v242, v59, v107
	v_mul_f32_e32 v243, v43, v107
	ds_write2_b32 v123, v242, v243 offset0:128 offset1:160
	v_mul_f32_e32 v244, v27, v107
	v_mul_f32_e32 v245, v11, v107
	ds_write2_b32 v123, v244, v245 offset0:192 offset1:224
	v_mul_f32_e32 v246, v60, v108
	v_mul_f32_e32 v247, v44, v108
	ds_write2_b32 v124, v246, v247 offset0:0 offset1:32
	v_mul_f32_e32 v248, v28, v108
	v_mul_f32_e32 v249, v12, v108
	ds_write2_b32 v124, v248, v249 offset0:64 offset1:96
	v_mul_f32_e32 v250, v61, v109
	v_mul_f32_e32 v251, v45, v109
	ds_write2_b32 v124, v250, v251 offset0:128 offset1:160
	v_mul_f32_e32 v252, v29, v109
	v_mul_f32_e32 v253, v13, v109
	ds_write2_b32 v124, v252, v253 offset0:192 offset1:224
	v_mul_f32_e32 v254, v62, v110
	v_mul_f32_e32 v255, v46, v110
	ds_write2_b32 v125, v254, v255 offset0:0 offset1:32
	v_mul_f32_e32 v146, v30, v110
	v_mul_f32_e32 v147, v14, v110
	ds_write2_b32 v125, v146, v147 offset0:64 offset1:96
	v_mul_f32_e32 v148, v63, v111
	v_mul_f32_e32 v149, v47, v111
	ds_write2_b32 v125, v148, v149 offset0:128 offset1:160
	v_mul_f32_e32 v150, v31, v111
	v_mul_f32_e32 v151, v15, v111
	ds_write2_b32 v125, v150, v151 offset0:192 offset1:224
	s_branch .Lde_join

.LBB0_807:
	v_mov_b32_e32 v96, v0
	v_mov_b32_e32 v97, v1
	v_mov_b32_e32 v98, v2
	v_mov_b32_e32 v99, v3
	v_mov_b32_e32 v100, v4
	v_mov_b32_e32 v101, v5
	v_mov_b32_e32 v102, v6
	v_mov_b32_e32 v103, v7
	v_mov_b32_e32 v104, v8
	v_mov_b32_e32 v105, v9
	v_mov_b32_e32 v106, v10
	v_mov_b32_e32 v107, v11
	v_mov_b32_e32 v108, v12
	v_mov_b32_e32 v109, v13
	v_mov_b32_e32 v110, v14
	v_mov_b32_e32 v111, v15
	v_add_u32_e32 v2, s36, v20
	v_mov_b64_e32 v[0:1], s[8:9]
	v_mad_i64_i32 v[0:1], s[36:37], v2, s89, v[0:1]
	v_and_b32_e32 v2, 7, v21
	s_add_u32 s36, s27, s92
	v_lshlrev_b32_e32 v2, 4, v2
	v_mov_b32_e32 v3, v147
	s_addc_u32 s37, 0, 0
	s_add_i32 s21, s21, s20
	v_lshl_add_u64 v[150:151], v[0:1], 0, v[2:3]
	v_add3_u32 v0, s21, v19, v18
	v_ashrrev_i32_e32 v1, 31, v0
	v_lshlrev_b64 v[0:1], 12, v[0:1]
	v_and_b32_e32 v2, 3, v16
	s_lshl_b32 s8, s0, 1
	v_lshl_add_u64 v[0:1], s[36:37], 0, v[0:1]
	v_lshlrev_b32_e32 v2, 4, v2
	s_and_b32 s8, s8, 0x80
	v_lshl_add_u64 v[0:1], v[0:1], 0, v[2:3]
	v_lshl_or_b32 v2, v163, 6, s8
	v_lshl_add_u64 v[152:153], v[0:1], 0, v[2:3]
	v_add_u32_e32 v0, s19, v17
	v_ashrrev_i32_e32 v1, 31, v0
	v_lshlrev_b64 v[0:1], 12, v[0:1]
	v_lshl_add_u64 v[0:1], s[36:37], 0, v[0:1]
	v_lshl_add_u64 v[154:155], v[0:1], 0, v[146:147]
	v_and_b32_e32 v149, 63, v16
	v_lshlrev_b32_e32 v0, 4, v162
	v_lshlrev_b32_e32 v23, 8, v162
	v_and_b32_e32 v52, 0xf0, v0
	v_or_b32_e32 v24, 0x0, v148
	v_xor_b32_e32 v24, v24, v52
	v_or_b32_e32 v24, v24, v23
	v_add_u32_e32 v242, 0xc000, v24
	v_or_b32_e32 v24, 0x20, v148
	v_xor_b32_e32 v24, v24, v52
	v_or_b32_e32 v24, v24, v23
	v_add_u32_e32 v243, 0xc000, v24
	v_or_b32_e32 v24, 0x40, v148
	v_xor_b32_e32 v24, v24, v52
	v_or_b32_e32 v24, v24, v23
	v_add_u32_e32 v244, 0xc000, v24
	v_or_b32_e32 v24, 0x60, v148
	v_xor_b32_e32 v24, v24, v52
	v_or_b32_e32 v24, v24, v23
	v_add_u32_e32 v245, 0xc000, v24
	v_or_b32_e32 v24, 0x80, v148
	v_xor_b32_e32 v24, v24, v52
	v_or_b32_e32 v24, v24, v23
	v_add_u32_e32 v246, 0xc000, v24
	v_or_b32_e32 v24, 0xa0, v148
	v_xor_b32_e32 v24, v24, v52
	v_or_b32_e32 v24, v24, v23
	v_add_u32_e32 v247, 0xc000, v24
	v_or_b32_e32 v24, 0xc0, v148
	v_xor_b32_e32 v24, v24, v52
	v_or_b32_e32 v24, v24, v23
	v_add_u32_e32 v248, 0xc000, v24
	v_or_b32_e32 v24, 0xe0, v148
	v_xor_b32_e32 v24, v24, v52
	v_or_b32_e32 v24, v24, v23
	v_add_u32_e32 v249, 0xc000, v24
	v_lshlrev_b32_e32 v25, 7, v162
	v_bfe_u32 v26, v16, 1, 3
	v_or_b32_e32 v24, 0, v163
	v_xor_b32_e32 v24, v24, v26
	v_lshl_or_b32 v24, v24, 4, v25
	v_add_u32_e32 v250, 0x14000, v24
	v_or_b32_e32 v24, 2, v163
	v_xor_b32_e32 v24, v24, v26
	v_lshl_or_b32 v24, v24, 4, v25
	v_add_u32_e32 v251, 0x14000, v24
	v_or_b32_e32 v24, 4, v163
	v_xor_b32_e32 v24, v24, v26
	v_lshl_or_b32 v24, v24, 4, v25
	v_add_u32_e32 v252, 0x14000, v24
	v_or_b32_e32 v24, 6, v163
	v_xor_b32_e32 v24, v24, v26
	v_lshl_or_b32 v24, v24, 4, v25
	v_add_u32_e32 v253, 0x14000, v24
	v_lshlrev_b32_e32 v24, 4, v149
	v_lshlrev_b32_e32 v25, 3, v149
	v_and_b32_e32 v26, 0xc0, v24
	v_and_or_b32 v24, v25, 24, v26
	v_lshlrev_b32_e32 v26, 1, v149
	v_and_b32_e32 v26, 32, v26
	v_and_b32_e32 v25, 0x100, v25
	v_or3_b32 v165, v24, v26, v25
	v_mov_b32_e32 v166, v165
	s_mov_b32 s14, 0x8000
	s_add_i32 s38, s5, 0x2000
	s_movk_i32 s15, 63
	v_mov_b32_e32 v0, 0
	v_mov_b32_e32 v1, 0
	v_mov_b32_e32 v2, 0
	v_mov_b32_e32 v3, 0
	v_mov_b32_e32 v4, 0
	v_mov_b32_e32 v5, 0
	v_mov_b32_e32 v6, 0
	v_mov_b32_e32 v7, 0
	v_mov_b32_e32 v8, 0
	v_mov_b32_e32 v9, 0
	v_mov_b32_e32 v10, 0
	v_mov_b32_e32 v11, 0
	v_mov_b32_e32 v12, 0
	v_mov_b32_e32 v13, 0
	v_mov_b32_e32 v14, 0
	v_mov_b32_e32 v15, 0
	v_mov_b32_e32 v16, 0
	v_mov_b32_e32 v17, 0
	v_mov_b32_e32 v18, 0
	v_mov_b32_e32 v19, 0
	v_mov_b32_e32 v20, 0
	v_mov_b32_e32 v21, 0
	v_mov_b32_e32 v22, 0
	v_mov_b32_e32 v23, 0
	v_mov_b32_e32 v24, 0
	v_mov_b32_e32 v25, 0
	v_mov_b32_e32 v26, 0
	v_mov_b32_e32 v27, 0
	v_mov_b32_e32 v28, 0
	v_mov_b32_e32 v29, 0
	v_mov_b32_e32 v30, 0
	v_mov_b32_e32 v31, 0
	v_mov_b32_e32 v32, 0
	v_mov_b32_e32 v33, 0
	v_mov_b32_e32 v34, 0
	v_mov_b32_e32 v35, 0
	v_mov_b32_e32 v36, 0
	v_mov_b32_e32 v37, 0
	v_mov_b32_e32 v38, 0
	v_mov_b32_e32 v39, 0
	v_mov_b32_e32 v40, 0
	v_mov_b32_e32 v41, 0
	v_mov_b32_e32 v42, 0
	v_mov_b32_e32 v43, 0
	v_mov_b32_e32 v44, 0
	v_mov_b32_e32 v45, 0
	v_mov_b32_e32 v46, 0
	v_mov_b32_e32 v47, 0
	v_mov_b32_e32 v48, 0
	v_mov_b32_e32 v49, 0
	v_mov_b32_e32 v50, 0
	v_mov_b32_e32 v51, 0
	v_mov_b32_e32 v52, 0
	v_mov_b32_e32 v53, 0
	v_mov_b32_e32 v54, 0
	v_mov_b32_e32 v55, 0
	v_mov_b32_e32 v56, 0
	v_mov_b32_e32 v57, 0
	v_mov_b32_e32 v58, 0
	v_mov_b32_e32 v59, 0
	v_mov_b32_e32 v60, 0
	v_mov_b32_e32 v61, 0
	v_mov_b32_e32 v62, 0
	v_mov_b32_e32 v63, 0
	v_mov_b32_e32 v254, 0
	v_mov_b32_e32 v255, 0
	s_waitcnt lgkmcnt(0)
	s_waitcnt vmcnt(0)
	s_barrier
	ds_read_b128 v[184:187], v242 offset:0
	ds_read_b128 v[188:191], v243 offset:0
	s_add_i32 s14, s14, 0x4000
	s_cmp_ge_u32 s14, 0xc000
	s_cselect_b32 s18, 0xc000, 0
	s_sub_i32 s14, s14, s18
	v_add_u32_e32 v166, s14, v165
	ds_read_b128 v[192:195], v244 offset:0
	ds_read_b128 v[196:199], v245 offset:0
	ds_read_b128 v[200:203], v246 offset:0
	ds_read_b128 v[204:207], v247 offset:0
	ds_read_b128 v[208:211], v248 offset:0
	s_waitcnt lgkmcnt(6)
	v_mfma_f32_32x32x16_bf16 v[64:79], v[184:187], v[140:143], 0
	ds_read_b128 v[184:187], v249 offset:0
	s_waitcnt lgkmcnt(6)
	v_mfma_f32_32x32x16_bf16 v[64:79], v[188:191], v[136:139], v[64:79]
	ds_read_b128 v[188:191], v250 offset:0
	s_waitcnt lgkmcnt(6)
	v_mfma_f32_32x32x16_bf16 v[64:79], v[192:195], v[132:135], v[64:79]
	ds_read_b128 v[192:195], v251 offset:0
	s_waitcnt lgkmcnt(6)
	v_mfma_f32_32x32x16_bf16 v[64:79], v[196:199], v[128:131], v[64:79]
	ds_read_b128 v[196:199], v252 offset:0
	s_waitcnt lgkmcnt(6)
	v_mfma_f32_32x32x16_bf16 v[64:79], v[200:203], v[124:127], v[64:79]
	ds_read_b128 v[200:203], v253 offset:0
	s_waitcnt lgkmcnt(6)
	v_mfma_f32_32x32x16_bf16 v[64:79], v[204:207], v[120:123], v[64:79]
	ds_read_b128 v[204:207], v242 offset:8192
	s_waitcnt lgkmcnt(6)
	v_mfma_f32_32x32x16_bf16 v[64:79], v[208:211], v[116:119], v[64:79]
	ds_read_b128 v[208:211], v243 offset:8192
	s_waitcnt lgkmcnt(6)
	v_mfma_f32_32x32x16_bf16 v[64:79], v[184:187], v[112:115], v[64:79]
	ds_read_b128 v[184:187], v244 offset:8192
	s_waitcnt lgkmcnt(6)
	v_mfma_f32_32x32x16_bf16 v[64:79], v[188:191], v[96:99], v[64:79]
	ds_read_b128 v[188:191], v245 offset:8192
	s_waitcnt lgkmcnt(6)
	v_mfma_f32_32x32x16_bf16 v[64:79], v[192:195], v[100:103], v[64:79]
	ds_read_b128 v[192:195], v246 offset:8192
	s_waitcnt lgkmcnt(6)
	v_mfma_f32_32x32x16_bf16 v[64:79], v[196:199], v[104:107], v[64:79]
	ds_read_b128 v[196:199], v247 offset:8192
	s_waitcnt lgkmcnt(6)
	v_mfma_f32_32x32x16_bf16 v[64:79], v[200:203], v[108:111], v[64:79]
	ds_read_b128 v[200:203], v248 offset:8192
	s_waitcnt lgkmcnt(6)
	v_mfma_f32_32x32x16_bf16 v[80:95], v[204:207], v[140:143], 0
	ds_read_b128 v[204:207], v249 offset:8192
	s_waitcnt lgkmcnt(6)
	v_mfma_f32_32x32x16_bf16 v[80:95], v[208:211], v[136:139], v[80:95]
	ds_read_b128 v[208:211], v250 offset:4096
	s_waitcnt lgkmcnt(6)
	v_mfma_f32_32x32x16_bf16 v[80:95], v[184:187], v[132:135], v[80:95]
	ds_read_b128 v[184:187], v251 offset:4096
	s_waitcnt lgkmcnt(6)
	v_mfma_f32_32x32x16_bf16 v[80:95], v[188:191], v[128:131], v[80:95]
	v_exp_f32_e32 v64, v64
	v_exp_f32_e32 v65, v65
	v_exp_f32_e32 v66, v66
	ds_read_b128 v[188:191], v252 offset:4096
	s_waitcnt lgkmcnt(6)
	v_mfma_f32_32x32x16_bf16 v[80:95], v[192:195], v[124:127], v[80:95]
	v_exp_f32_e32 v67, v67
	v_pk_add_f32 v[254:255], v[254:255], v[64:65]
	v_exp_f32_e32 v68, v68
	ds_read_b128 v[192:195], v253 offset:4096
	s_waitcnt lgkmcnt(6)
	v_mfma_f32_32x32x16_bf16 v[80:95], v[196:199], v[120:123], v[80:95]
	v_exp_f32_e32 v69, v69
	v_pk_add_f32 v[254:255], v[254:255], v[66:67]
	v_exp_f32_e32 v70, v70
	ds_read_b64_tr_b16 v[212:213], v166 offset:0
	ds_read_b64_tr_b16 v[214:215], v166 offset:2048
	s_waitcnt lgkmcnt(7)
	v_mfma_f32_32x32x16_bf16 v[80:95], v[200:203], v[116:119], v[80:95]
	v_exp_f32_e32 v71, v71
	v_pk_add_f32 v[254:255], v[254:255], v[68:69]
	v_pk_add_f32 v[254:255], v[254:255], v[70:71]
	ds_read_b64_tr_b16 v[216:217], v166 offset:512
	ds_read_b64_tr_b16 v[218:219], v166 offset:2560
	s_waitcnt lgkmcnt(8)
	v_mfma_f32_32x32x16_bf16 v[80:95], v[204:207], v[112:115], v[80:95]
	v_cvt_pk_bf16_f32 v168, v64, v65
	v_cvt_pk_bf16_f32 v170, v68, v69
	v_cvt_pk_bf16_f32 v169, v66, v67
	v_cvt_pk_bf16_f32 v171, v70, v71
	ds_read_b64_tr_b16 v[220:221], v166 offset:1024
	ds_read_b64_tr_b16 v[222:223], v166 offset:3072
	s_waitcnt lgkmcnt(9)
	v_mfma_f32_32x32x16_bf16 v[80:95], v[208:211], v[96:99], v[80:95]
	v_exp_f32_e32 v72, v72
	v_exp_f32_e32 v73, v73
	v_exp_f32_e32 v74, v74
	ds_read_b64_tr_b16 v[224:225], v166 offset:1536
	ds_read_b64_tr_b16 v[226:227], v166 offset:3584
	s_waitcnt lgkmcnt(10)
	v_mfma_f32_32x32x16_bf16 v[80:95], v[184:187], v[100:103], v[80:95]
	v_exp_f32_e32 v75, v75
	v_pk_add_f32 v[254:255], v[254:255], v[72:73]
	v_exp_f32_e32 v76, v76
	v_exp_f32_e32 v77, v77
	ds_read_b64_tr_b16 v[228:229], v166 offset:4096
	ds_read_b64_tr_b16 v[230:231], v166 offset:6144
	s_waitcnt lgkmcnt(11)
	v_mfma_f32_32x32x16_bf16 v[80:95], v[188:191], v[104:107], v[80:95]
	v_pk_add_f32 v[254:255], v[254:255], v[74:75]
	v_exp_f32_e32 v78, v78
	v_exp_f32_e32 v79, v79
	ds_read_b64_tr_b16 v[232:233], v166 offset:4608
	ds_read_b64_tr_b16 v[234:235], v166 offset:6656
	s_waitcnt lgkmcnt(12)
	v_mfma_f32_32x32x16_bf16 v[80:95], v[192:195], v[108:111], v[80:95]
	v_pk_add_f32 v[254:255], v[254:255], v[76:77]
	v_pk_add_f32 v[254:255], v[254:255], v[78:79]
	v_cvt_pk_bf16_f32 v172, v72, v73
	v_cvt_pk_bf16_f32 v174, v76, v77
	v_cvt_pk_bf16_f32 v173, v74, v75
	v_cvt_pk_bf16_f32 v175, v78, v79
.Lmla_loop:
	s_waitcnt vmcnt(0)
	s_barrier
	s_add_i32 s37, s14, 0x8000
	s_cmp_ge_u32 s37, 0xc000
	s_cselect_b32 s18, 0xc000, 0
	s_sub_i32 s37, s37, s18
	ds_read_b64_tr_b16 v[238:239], v166 offset:5120
	ds_read_b64_tr_b16 v[240:241], v166 offset:7168
	s_add_i32 m0, s5, 0xc000
	s_add_u32 s46, s28, s64
	s_addc_u32 s47, s29, s65
	global_load_lds_dwordx4 v154, s[46:47]
	s_waitcnt lgkmcnt(12)
	v_mfma_f32_32x32x16_bf16 v[48:63], v[168:171], v[212:215], v[48:63]
	v_exp_f32_e32 v80, v80
	v_exp_f32_e32 v81, v81
	v_exp_f32_e32 v82, v82
	ds_read_b64_tr_b16 v[212:213], v166 offset:5632
	ds_read_b64_tr_b16 v[214:215], v166 offset:7680
	s_add_i32 m0, s5, 0xe000
	s_add_u32 s46, s28, s66
	s_addc_u32 s47, s29, s67
	global_load_lds_dwordx4 v154, s[46:47]
	s_waitcnt lgkmcnt(12)
	v_mfma_f32_32x32x16_bf16 v[32:47], v[168:171], v[216:219], v[32:47]
	v_exp_f32_e32 v83, v83
	v_pk_add_f32 v[254:255], v[254:255], v[80:81]
	v_exp_f32_e32 v84, v84
	ds_read_b64_tr_b16 v[216:217], v166 offset:8192
	ds_read_b64_tr_b16 v[218:219], v166 offset:10240
	s_add_i32 m0, s5, s37
	s_add_u32 s46, s28, s68
	s_addc_u32 s47, s29, s69
	global_load_lds_dwordx4 v152, s[46:47]
	s_waitcnt lgkmcnt(12)
	v_mfma_f32_32x32x16_bf16 v[16:31], v[168:171], v[220:223], v[16:31]
	v_exp_f32_e32 v85, v85
	v_pk_add_f32 v[254:255], v[254:255], v[82:83]
	v_exp_f32_e32 v86, v86
	ds_read_b64_tr_b16 v[220:221], v166 offset:8704
	ds_read_b64_tr_b16 v[222:223], v166 offset:10752
	s_add_i32 m0, s37, s38
	s_add_u32 s46, s28, s70
	s_addc_u32 s47, s29, s71
	global_load_lds_dwordx4 v152, s[46:47]
	s_waitcnt lgkmcnt(12)
	v_mfma_f32_32x32x16_bf16 v[0:15], v[168:171], v[224:227], v[0:15]
	v_exp_f32_e32 v87, v87
	v_pk_add_f32 v[254:255], v[254:255], v[84:85]
	v_pk_add_f32 v[254:255], v[254:255], v[86:87]
	ds_read_b64_tr_b16 v[224:225], v166 offset:9216
	ds_read_b64_tr_b16 v[226:227], v166 offset:11264
	s_add_i32 m0, s5, 0x14000
	s_add_u32 s46, s28, s72
	s_addc_u32 s47, s29, s73
	global_load_lds_dwordx4 v150, s[46:47]
	s_waitcnt lgkmcnt(12)
	v_mfma_f32_32x32x16_bf16 v[48:63], v[172:175], v[228:231], v[48:63]
	v_cvt_pk_bf16_f32 v176, v80, v81
	v_cvt_pk_bf16_f32 v178, v84, v85
	v_cvt_pk_bf16_f32 v177, v82, v83
	v_cvt_pk_bf16_f32 v179, v86, v87
	ds_read_b64_tr_b16 v[228:229], v166 offset:9728
	ds_read_b64_tr_b16 v[230:231], v166 offset:11776
	s_waitcnt lgkmcnt(12)
	v_mfma_f32_32x32x16_bf16 v[32:47], v[172:175], v[232:235], v[32:47]
	v_exp_f32_e32 v88, v88
	v_exp_f32_e32 v89, v89
	ds_read_b64_tr_b16 v[232:233], v166 offset:12288
	ds_read_b64_tr_b16 v[234:235], v166 offset:14336
	s_waitcnt lgkmcnt(12)
	v_mfma_f32_32x32x16_bf16 v[16:31], v[172:175], v[238:241], v[16:31]
	v_exp_f32_e32 v90, v90
	v_exp_f32_e32 v91, v91
	ds_read_b64_tr_b16 v[238:239], v166 offset:12800
	ds_read_b64_tr_b16 v[240:241], v166 offset:14848
	s_waitcnt lgkmcnt(12)
	v_mfma_f32_32x32x16_bf16 v[0:15], v[172:175], v[212:215], v[0:15]
	v_pk_add_f32 v[254:255], v[254:255], v[88:89]
	v_exp_f32_e32 v92, v92
	v_exp_f32_e32 v93, v93
	ds_read_b64_tr_b16 v[212:213], v166 offset:13312
	ds_read_b64_tr_b16 v[214:215], v166 offset:15360
	s_waitcnt lgkmcnt(12)
	v_mfma_f32_32x32x16_bf16 v[48:63], v[176:179], v[216:219], v[48:63]
	v_pk_add_f32 v[254:255], v[254:255], v[90:91]
	v_exp_f32_e32 v94, v94
	ds_read_b64_tr_b16 v[216:217], v166 offset:13824
	ds_read_b64_tr_b16 v[218:219], v166 offset:15872
	s_waitcnt lgkmcnt(12)
	v_mfma_f32_32x32x16_bf16 v[32:47], v[176:179], v[220:223], v[32:47]
	v_exp_f32_e32 v95, v95
	v_pk_add_f32 v[254:255], v[254:255], v[92:93]
	v_pk_add_f32 v[254:255], v[254:255], v[94:95]
	ds_read_b128 v[184:187], v242 offset:16384
	s_waitcnt lgkmcnt(11)
	v_mfma_f32_32x32x16_bf16 v[16:31], v[176:179], v[224:227], v[16:31]
	v_cvt_pk_bf16_f32 v180, v88, v89
	v_cvt_pk_bf16_f32 v182, v92, v93
	v_cvt_pk_bf16_f32 v181, v90, v91
	v_cvt_pk_bf16_f32 v183, v94, v95
	ds_read_b128 v[188:191], v243 offset:16384
	s_waitcnt lgkmcnt(10)
	v_mfma_f32_32x32x16_bf16 v[0:15], v[176:179], v[228:231], v[0:15]
	s_add_i32 s14, s14, 0x4000
	s_cmp_ge_u32 s14, 0xc000
	s_cselect_b32 s18, 0xc000, 0
	s_sub_i32 s14, s14, s18
	v_add_u32_e32 v166, s14, v165
	ds_read_b128 v[192:195], v244 offset:16384
	s_waitcnt lgkmcnt(9)
	v_mfma_f32_32x32x16_bf16 v[48:63], v[180:183], v[232:235], v[48:63]
	ds_read_b128 v[196:199], v245 offset:16384
	s_waitcnt lgkmcnt(8)
	v_mfma_f32_32x32x16_bf16 v[32:47], v[180:183], v[238:241], v[32:47]
	ds_read_b128 v[200:203], v246 offset:16384
	s_waitcnt lgkmcnt(7)
	v_mfma_f32_32x32x16_bf16 v[16:31], v[180:183], v[212:215], v[16:31]
	ds_read_b128 v[204:207], v247 offset:16384
	s_waitcnt lgkmcnt(6)
	v_mfma_f32_32x32x16_bf16 v[0:15], v[180:183], v[216:219], v[0:15]
	ds_read_b128 v[208:211], v248 offset:16384
	s_waitcnt lgkmcnt(6)
	v_mfma_f32_32x32x16_bf16 v[64:79], v[184:187], v[140:143], 0
	ds_read_b128 v[184:187], v249 offset:16384
	s_waitcnt lgkmcnt(6)
	v_mfma_f32_32x32x16_bf16 v[64:79], v[188:191], v[136:139], v[64:79]
	ds_read_b128 v[188:191], v250 offset:8192
	s_waitcnt lgkmcnt(6)
	v_mfma_f32_32x32x16_bf16 v[64:79], v[192:195], v[132:135], v[64:79]
	ds_read_b128 v[192:195], v251 offset:8192
	s_waitcnt lgkmcnt(6)
	v_mfma_f32_32x32x16_bf16 v[64:79], v[196:199], v[128:131], v[64:79]
	ds_read_b128 v[196:199], v252 offset:8192
	s_waitcnt lgkmcnt(6)
	v_mfma_f32_32x32x16_bf16 v[64:79], v[200:203], v[124:127], v[64:79]
	ds_read_b128 v[200:203], v253 offset:8192
	s_waitcnt lgkmcnt(6)
	v_mfma_f32_32x32x16_bf16 v[64:79], v[204:207], v[120:123], v[64:79]
	ds_read_b128 v[204:207], v242 offset:24576
	s_waitcnt lgkmcnt(6)
	v_mfma_f32_32x32x16_bf16 v[64:79], v[208:211], v[116:119], v[64:79]
	ds_read_b128 v[208:211], v243 offset:24576
	s_waitcnt lgkmcnt(6)
	v_mfma_f32_32x32x16_bf16 v[64:79], v[184:187], v[112:115], v[64:79]
	ds_read_b128 v[184:187], v244 offset:24576
	s_waitcnt lgkmcnt(6)
	v_mfma_f32_32x32x16_bf16 v[64:79], v[188:191], v[96:99], v[64:79]
	ds_read_b128 v[188:191], v245 offset:24576
	s_waitcnt lgkmcnt(6)
	v_mfma_f32_32x32x16_bf16 v[64:79], v[192:195], v[100:103], v[64:79]
	ds_read_b128 v[192:195], v246 offset:24576
	s_waitcnt lgkmcnt(6)
	v_mfma_f32_32x32x16_bf16 v[64:79], v[196:199], v[104:107], v[64:79]
	ds_read_b128 v[196:199], v247 offset:24576
	s_waitcnt lgkmcnt(6)
	v_mfma_f32_32x32x16_bf16 v[64:79], v[200:203], v[108:111], v[64:79]
	ds_read_b128 v[200:203], v248 offset:24576
	s_waitcnt lgkmcnt(6)
	v_mfma_f32_32x32x16_bf16 v[80:95], v[204:207], v[140:143], 0
	ds_read_b128 v[204:207], v249 offset:24576
	s_waitcnt lgkmcnt(6)
	v_mfma_f32_32x32x16_bf16 v[80:95], v[208:211], v[136:139], v[80:95]
	ds_read_b128 v[208:211], v250 offset:12288
	s_waitcnt lgkmcnt(6)
	v_mfma_f32_32x32x16_bf16 v[80:95], v[184:187], v[132:135], v[80:95]
	ds_read_b128 v[184:187], v251 offset:12288
	s_waitcnt lgkmcnt(6)
	v_mfma_f32_32x32x16_bf16 v[80:95], v[188:191], v[128:131], v[80:95]
	v_exp_f32_e32 v64, v64
	v_exp_f32_e32 v65, v65
	v_exp_f32_e32 v66, v66
	ds_read_b128 v[188:191], v252 offset:12288
	s_waitcnt lgkmcnt(6)
	v_mfma_f32_32x32x16_bf16 v[80:95], v[192:195], v[124:127], v[80:95]
	v_exp_f32_e32 v67, v67
	v_pk_add_f32 v[254:255], v[254:255], v[64:65]
	v_exp_f32_e32 v68, v68
	ds_read_b128 v[192:195], v253 offset:12288
	s_waitcnt lgkmcnt(6)
	v_mfma_f32_32x32x16_bf16 v[80:95], v[196:199], v[120:123], v[80:95]
	v_exp_f32_e32 v69, v69
	v_pk_add_f32 v[254:255], v[254:255], v[66:67]
	v_exp_f32_e32 v70, v70
	ds_read_b64_tr_b16 v[212:213], v166 offset:0
	ds_read_b64_tr_b16 v[214:215], v166 offset:2048
	s_waitcnt lgkmcnt(7)
	v_mfma_f32_32x32x16_bf16 v[80:95], v[200:203], v[116:119], v[80:95]
	v_exp_f32_e32 v71, v71
	v_pk_add_f32 v[254:255], v[254:255], v[68:69]
	v_pk_add_f32 v[254:255], v[254:255], v[70:71]
	ds_read_b64_tr_b16 v[216:217], v166 offset:512
	ds_read_b64_tr_b16 v[218:219], v166 offset:2560
	s_waitcnt lgkmcnt(8)
	v_mfma_f32_32x32x16_bf16 v[80:95], v[204:207], v[112:115], v[80:95]
	v_cvt_pk_bf16_f32 v168, v64, v65
	v_cvt_pk_bf16_f32 v170, v68, v69
	v_cvt_pk_bf16_f32 v169, v66, v67
	v_cvt_pk_bf16_f32 v171, v70, v71
	ds_read_b64_tr_b16 v[220:221], v166 offset:1024
	ds_read_b64_tr_b16 v[222:223], v166 offset:3072
	s_waitcnt lgkmcnt(9)
	v_mfma_f32_32x32x16_bf16 v[80:95], v[208:211], v[96:99], v[80:95]
	v_exp_f32_e32 v72, v72
	v_exp_f32_e32 v73, v73
	v_exp_f32_e32 v74, v74
	ds_read_b64_tr_b16 v[224:225], v166 offset:1536
	ds_read_b64_tr_b16 v[226:227], v166 offset:3584
	s_waitcnt lgkmcnt(10)
	v_mfma_f32_32x32x16_bf16 v[80:95], v[184:187], v[100:103], v[80:95]
	v_exp_f32_e32 v75, v75
	v_pk_add_f32 v[254:255], v[254:255], v[72:73]
	v_exp_f32_e32 v76, v76
	v_exp_f32_e32 v77, v77
	ds_read_b64_tr_b16 v[228:229], v166 offset:4096
	ds_read_b64_tr_b16 v[230:231], v166 offset:6144
	s_waitcnt lgkmcnt(11)
	v_mfma_f32_32x32x16_bf16 v[80:95], v[188:191], v[104:107], v[80:95]
	v_pk_add_f32 v[254:255], v[254:255], v[74:75]
	v_exp_f32_e32 v78, v78
	v_exp_f32_e32 v79, v79
	ds_read_b64_tr_b16 v[232:233], v166 offset:4608
	ds_read_b64_tr_b16 v[234:235], v166 offset:6656
	s_waitcnt lgkmcnt(12)
	v_mfma_f32_32x32x16_bf16 v[80:95], v[192:195], v[108:111], v[80:95]
	v_pk_add_f32 v[254:255], v[254:255], v[76:77]
	v_pk_add_f32 v[254:255], v[254:255], v[78:79]
	v_cvt_pk_bf16_f32 v172, v72, v73
	v_cvt_pk_bf16_f32 v174, v76, v77
	v_cvt_pk_bf16_f32 v173, v74, v75
	v_cvt_pk_bf16_f32 v175, v78, v79
	s_waitcnt vmcnt(0)
	s_barrier
	s_add_i32 s37, s14, 0x8000
	s_cmp_ge_u32 s37, 0xc000
	s_cselect_b32 s18, 0xc000, 0
	s_sub_i32 s37, s37, s18
	ds_read_b64_tr_b16 v[238:239], v166 offset:5120
	ds_read_b64_tr_b16 v[240:241], v166 offset:7168
	s_add_i32 m0, s5, 0x10000
	s_add_u32 s46, s28, s74
	s_addc_u32 s47, s29, s75
	global_load_lds_dwordx4 v154, s[46:47]
	s_waitcnt lgkmcnt(12)
	v_mfma_f32_32x32x16_bf16 v[48:63], v[168:171], v[212:215], v[48:63]
	v_exp_f32_e32 v80, v80
	v_exp_f32_e32 v81, v81
	v_exp_f32_e32 v82, v82
	ds_read_b64_tr_b16 v[212:213], v166 offset:5632
	ds_read_b64_tr_b16 v[214:215], v166 offset:7680
	s_add_i32 m0, s5, 0x12000
	s_add_u32 s46, s28, s76
	s_addc_u32 s47, s29, s77
	global_load_lds_dwordx4 v154, s[46:47]
	s_waitcnt lgkmcnt(12)
	v_mfma_f32_32x32x16_bf16 v[32:47], v[168:171], v[216:219], v[32:47]
	v_exp_f32_e32 v83, v83
	v_pk_add_f32 v[254:255], v[254:255], v[80:81]
	v_exp_f32_e32 v84, v84
	ds_read_b64_tr_b16 v[216:217], v166 offset:8192
	ds_read_b64_tr_b16 v[218:219], v166 offset:10240
	s_add_i32 m0, s5, s37
	s_add_u32 s46, s28, s78
	s_addc_u32 s47, s29, s79
	global_load_lds_dwordx4 v152, s[46:47]
	s_waitcnt lgkmcnt(12)
	v_mfma_f32_32x32x16_bf16 v[16:31], v[168:171], v[220:223], v[16:31]
	v_exp_f32_e32 v85, v85
	v_pk_add_f32 v[254:255], v[254:255], v[82:83]
	v_exp_f32_e32 v86, v86
	ds_read_b64_tr_b16 v[220:221], v166 offset:8704
	ds_read_b64_tr_b16 v[222:223], v166 offset:10752
	s_add_i32 m0, s37, s38
	s_add_u32 s46, s28, s80
	s_addc_u32 s47, s29, s81
	global_load_lds_dwordx4 v152, s[46:47]
	s_waitcnt lgkmcnt(12)
	v_mfma_f32_32x32x16_bf16 v[0:15], v[168:171], v[224:227], v[0:15]
	v_exp_f32_e32 v87, v87
	v_pk_add_f32 v[254:255], v[254:255], v[84:85]
	v_pk_add_f32 v[254:255], v[254:255], v[86:87]
	ds_read_b64_tr_b16 v[224:225], v166 offset:9216
	ds_read_b64_tr_b16 v[226:227], v166 offset:11264
	s_add_i32 m0, s5, 0x16000
	s_add_u32 s46, s28, s82
	s_addc_u32 s47, s29, s83
	global_load_lds_dwordx4 v150, s[46:47]
	s_waitcnt lgkmcnt(12)
	v_mfma_f32_32x32x16_bf16 v[48:63], v[172:175], v[228:231], v[48:63]
	v_cvt_pk_bf16_f32 v176, v80, v81
	v_cvt_pk_bf16_f32 v178, v84, v85
	v_cvt_pk_bf16_f32 v177, v82, v83
	v_cvt_pk_bf16_f32 v179, v86, v87
	ds_read_b64_tr_b16 v[228:229], v166 offset:9728
	ds_read_b64_tr_b16 v[230:231], v166 offset:11776
	s_waitcnt lgkmcnt(12)
	v_mfma_f32_32x32x16_bf16 v[32:47], v[172:175], v[232:235], v[32:47]
	v_exp_f32_e32 v88, v88
	v_exp_f32_e32 v89, v89
	ds_read_b64_tr_b16 v[232:233], v166 offset:12288
	ds_read_b64_tr_b16 v[234:235], v166 offset:14336
	s_waitcnt lgkmcnt(12)
	v_mfma_f32_32x32x16_bf16 v[16:31], v[172:175], v[238:241], v[16:31]
	v_exp_f32_e32 v90, v90
	v_exp_f32_e32 v91, v91
	ds_read_b64_tr_b16 v[238:239], v166 offset:12800
	ds_read_b64_tr_b16 v[240:241], v166 offset:14848
	s_waitcnt lgkmcnt(12)
	v_mfma_f32_32x32x16_bf16 v[0:15], v[172:175], v[212:215], v[0:15]
	v_pk_add_f32 v[254:255], v[254:255], v[88:89]
	v_exp_f32_e32 v92, v92
	v_exp_f32_e32 v93, v93
	ds_read_b64_tr_b16 v[212:213], v166 offset:13312
	ds_read_b64_tr_b16 v[214:215], v166 offset:15360
	s_waitcnt lgkmcnt(12)
	v_mfma_f32_32x32x16_bf16 v[48:63], v[176:179], v[216:219], v[48:63]
	v_pk_add_f32 v[254:255], v[254:255], v[90:91]
	v_exp_f32_e32 v94, v94
	ds_read_b64_tr_b16 v[216:217], v166 offset:13824
	ds_read_b64_tr_b16 v[218:219], v166 offset:15872
	s_waitcnt lgkmcnt(12)
	v_mfma_f32_32x32x16_bf16 v[32:47], v[176:179], v[220:223], v[32:47]
	v_exp_f32_e32 v95, v95
	v_pk_add_f32 v[254:255], v[254:255], v[92:93]
	v_pk_add_f32 v[254:255], v[254:255], v[94:95]
	ds_read_b128 v[184:187], v242 offset:0
	s_waitcnt lgkmcnt(11)
	v_mfma_f32_32x32x16_bf16 v[16:31], v[176:179], v[224:227], v[16:31]
	v_cvt_pk_bf16_f32 v180, v88, v89
	v_cvt_pk_bf16_f32 v182, v92, v93
	v_cvt_pk_bf16_f32 v181, v90, v91
	v_cvt_pk_bf16_f32 v183, v94, v95
	ds_read_b128 v[188:191], v243 offset:0
	s_waitcnt lgkmcnt(10)
	v_mfma_f32_32x32x16_bf16 v[0:15], v[176:179], v[228:231], v[0:15]
	s_add_i32 s14, s14, 0x4000
	s_cmp_ge_u32 s14, 0xc000
	s_cselect_b32 s18, 0xc000, 0
	s_sub_i32 s14, s14, s18
	v_add_u32_e32 v166, s14, v165
	ds_read_b128 v[192:195], v244 offset:0
	s_waitcnt lgkmcnt(9)
	v_mfma_f32_32x32x16_bf16 v[48:63], v[180:183], v[232:235], v[48:63]
	ds_read_b128 v[196:199], v245 offset:0
	s_waitcnt lgkmcnt(8)
	v_mfma_f32_32x32x16_bf16 v[32:47], v[180:183], v[238:241], v[32:47]
	ds_read_b128 v[200:203], v246 offset:0
	s_waitcnt lgkmcnt(7)
	v_mfma_f32_32x32x16_bf16 v[16:31], v[180:183], v[212:215], v[16:31]
	ds_read_b128 v[204:207], v247 offset:0
	s_waitcnt lgkmcnt(6)
	v_mfma_f32_32x32x16_bf16 v[0:15], v[180:183], v[216:219], v[0:15]
	ds_read_b128 v[208:211], v248 offset:0
	s_waitcnt lgkmcnt(6)
	v_mfma_f32_32x32x16_bf16 v[64:79], v[184:187], v[140:143], 0
	ds_read_b128 v[184:187], v249 offset:0
	s_waitcnt lgkmcnt(6)
	v_mfma_f32_32x32x16_bf16 v[64:79], v[188:191], v[136:139], v[64:79]
	ds_read_b128 v[188:191], v250 offset:0
	s_waitcnt lgkmcnt(6)
	v_mfma_f32_32x32x16_bf16 v[64:79], v[192:195], v[132:135], v[64:79]
	ds_read_b128 v[192:195], v251 offset:0
	s_waitcnt lgkmcnt(6)
	v_mfma_f32_32x32x16_bf16 v[64:79], v[196:199], v[128:131], v[64:79]
	ds_read_b128 v[196:199], v252 offset:0
	s_waitcnt lgkmcnt(6)
	v_mfma_f32_32x32x16_bf16 v[64:79], v[200:203], v[124:127], v[64:79]
	ds_read_b128 v[200:203], v253 offset:0
	s_waitcnt lgkmcnt(6)
	v_mfma_f32_32x32x16_bf16 v[64:79], v[204:207], v[120:123], v[64:79]
	ds_read_b128 v[204:207], v242 offset:8192
	s_waitcnt lgkmcnt(6)
	v_mfma_f32_32x32x16_bf16 v[64:79], v[208:211], v[116:119], v[64:79]
	ds_read_b128 v[208:211], v243 offset:8192
	s_waitcnt lgkmcnt(6)
	v_mfma_f32_32x32x16_bf16 v[64:79], v[184:187], v[112:115], v[64:79]
	ds_read_b128 v[184:187], v244 offset:8192
	s_waitcnt lgkmcnt(6)
	v_mfma_f32_32x32x16_bf16 v[64:79], v[188:191], v[96:99], v[64:79]
	ds_read_b128 v[188:191], v245 offset:8192
	s_waitcnt lgkmcnt(6)
	v_mfma_f32_32x32x16_bf16 v[64:79], v[192:195], v[100:103], v[64:79]
	ds_read_b128 v[192:195], v246 offset:8192
	s_waitcnt lgkmcnt(6)
	v_mfma_f32_32x32x16_bf16 v[64:79], v[196:199], v[104:107], v[64:79]
	ds_read_b128 v[196:199], v247 offset:8192
	s_waitcnt lgkmcnt(6)
	v_mfma_f32_32x32x16_bf16 v[64:79], v[200:203], v[108:111], v[64:79]
	ds_read_b128 v[200:203], v248 offset:8192
	s_waitcnt lgkmcnt(6)
	v_mfma_f32_32x32x16_bf16 v[80:95], v[204:207], v[140:143], 0
	ds_read_b128 v[204:207], v249 offset:8192
	s_waitcnt lgkmcnt(6)
	v_mfma_f32_32x32x16_bf16 v[80:95], v[208:211], v[136:139], v[80:95]
	ds_read_b128 v[208:211], v250 offset:4096
	s_waitcnt lgkmcnt(6)
	v_mfma_f32_32x32x16_bf16 v[80:95], v[184:187], v[132:135], v[80:95]
	ds_read_b128 v[184:187], v251 offset:4096
	s_waitcnt lgkmcnt(6)
	v_mfma_f32_32x32x16_bf16 v[80:95], v[188:191], v[128:131], v[80:95]
	v_exp_f32_e32 v64, v64
	v_exp_f32_e32 v65, v65
	v_exp_f32_e32 v66, v66
	ds_read_b128 v[188:191], v252 offset:4096
	s_waitcnt lgkmcnt(6)
	v_mfma_f32_32x32x16_bf16 v[80:95], v[192:195], v[124:127], v[80:95]
	v_exp_f32_e32 v67, v67
	v_pk_add_f32 v[254:255], v[254:255], v[64:65]
	v_exp_f32_e32 v68, v68
	ds_read_b128 v[192:195], v253 offset:4096
	s_waitcnt lgkmcnt(6)
	v_mfma_f32_32x32x16_bf16 v[80:95], v[196:199], v[120:123], v[80:95]
	v_exp_f32_e32 v69, v69
	v_pk_add_f32 v[254:255], v[254:255], v[66:67]
	v_exp_f32_e32 v70, v70
	ds_read_b64_tr_b16 v[212:213], v166 offset:0
	ds_read_b64_tr_b16 v[214:215], v166 offset:2048
	s_waitcnt lgkmcnt(7)
	v_mfma_f32_32x32x16_bf16 v[80:95], v[200:203], v[116:119], v[80:95]
	v_exp_f32_e32 v71, v71
	v_pk_add_f32 v[254:255], v[254:255], v[68:69]
	v_pk_add_f32 v[254:255], v[254:255], v[70:71]
	ds_read_b64_tr_b16 v[216:217], v166 offset:512
	ds_read_b64_tr_b16 v[218:219], v166 offset:2560
	s_waitcnt lgkmcnt(8)
	v_mfma_f32_32x32x16_bf16 v[80:95], v[204:207], v[112:115], v[80:95]
	v_cvt_pk_bf16_f32 v168, v64, v65
	v_cvt_pk_bf16_f32 v170, v68, v69
	v_cvt_pk_bf16_f32 v169, v66, v67
	v_cvt_pk_bf16_f32 v171, v70, v71
	ds_read_b64_tr_b16 v[220:221], v166 offset:1024
	ds_read_b64_tr_b16 v[222:223], v166 offset:3072
	s_waitcnt lgkmcnt(9)
	v_mfma_f32_32x32x16_bf16 v[80:95], v[208:211], v[96:99], v[80:95]
	v_exp_f32_e32 v72, v72
	v_exp_f32_e32 v73, v73
	v_exp_f32_e32 v74, v74
	ds_read_b64_tr_b16 v[224:225], v166 offset:1536
	ds_read_b64_tr_b16 v[226:227], v166 offset:3584
	s_waitcnt lgkmcnt(10)
	v_mfma_f32_32x32x16_bf16 v[80:95], v[184:187], v[100:103], v[80:95]
	v_exp_f32_e32 v75, v75
	v_pk_add_f32 v[254:255], v[254:255], v[72:73]
	v_exp_f32_e32 v76, v76
	v_exp_f32_e32 v77, v77
	ds_read_b64_tr_b16 v[228:229], v166 offset:4096
	ds_read_b64_tr_b16 v[230:231], v166 offset:6144
	s_waitcnt lgkmcnt(11)
	v_mfma_f32_32x32x16_bf16 v[80:95], v[188:191], v[104:107], v[80:95]
	v_pk_add_f32 v[254:255], v[254:255], v[74:75]
	v_exp_f32_e32 v78, v78
	v_exp_f32_e32 v79, v79
	ds_read_b64_tr_b16 v[232:233], v166 offset:4608
	ds_read_b64_tr_b16 v[234:235], v166 offset:6656
	s_waitcnt lgkmcnt(12)
	v_mfma_f32_32x32x16_bf16 v[80:95], v[192:195], v[108:111], v[80:95]
	v_pk_add_f32 v[254:255], v[254:255], v[76:77]
	v_pk_add_f32 v[254:255], v[254:255], v[78:79]
	v_cvt_pk_bf16_f32 v172, v72, v73
	v_cvt_pk_bf16_f32 v174, v76, v77
	v_cvt_pk_bf16_f32 v173, v74, v75
	v_cvt_pk_bf16_f32 v175, v78, v79
	v_add_u32_e32 v150, s84, v150
	v_add_u32_e32 v152, s86, v152
	v_add_u32_e32 v154, s86, v154
	s_sub_i32 s15, s15, 1
	s_cmp_lg_u32 s15, 0
	s_cbranch_scc1 .Lmla_loop
	s_waitcnt vmcnt(0)
	s_barrier
	ds_read_b64_tr_b16 v[238:239], v166 offset:5120
	ds_read_b64_tr_b16 v[240:241], v166 offset:7168
	s_waitcnt lgkmcnt(12)
	v_mfma_f32_32x32x16_bf16 v[48:63], v[168:171], v[212:215], v[48:63]
	v_exp_f32_e32 v80, v80
	v_exp_f32_e32 v81, v81
	v_exp_f32_e32 v82, v82
	ds_read_b64_tr_b16 v[212:213], v166 offset:5632
	ds_read_b64_tr_b16 v[214:215], v166 offset:7680
	s_waitcnt lgkmcnt(12)
	v_mfma_f32_32x32x16_bf16 v[32:47], v[168:171], v[216:219], v[32:47]
	v_exp_f32_e32 v83, v83
	v_pk_add_f32 v[254:255], v[254:255], v[80:81]
	v_exp_f32_e32 v84, v84
	ds_read_b64_tr_b16 v[216:217], v166 offset:8192
	ds_read_b64_tr_b16 v[218:219], v166 offset:10240
	s_waitcnt lgkmcnt(12)
	v_mfma_f32_32x32x16_bf16 v[16:31], v[168:171], v[220:223], v[16:31]
	v_exp_f32_e32 v85, v85
	v_pk_add_f32 v[254:255], v[254:255], v[82:83]
	v_exp_f32_e32 v86, v86
	ds_read_b64_tr_b16 v[220:221], v166 offset:8704
	ds_read_b64_tr_b16 v[222:223], v166 offset:10752
	s_waitcnt lgkmcnt(12)
	v_mfma_f32_32x32x16_bf16 v[0:15], v[168:171], v[224:227], v[0:15]
	v_exp_f32_e32 v87, v87
	v_pk_add_f32 v[254:255], v[254:255], v[84:85]
	v_pk_add_f32 v[254:255], v[254:255], v[86:87]
	ds_read_b64_tr_b16 v[224:225], v166 offset:9216
	ds_read_b64_tr_b16 v[226:227], v166 offset:11264
	s_waitcnt lgkmcnt(12)
	v_mfma_f32_32x32x16_bf16 v[48:63], v[172:175], v[228:231], v[48:63]
	v_cvt_pk_bf16_f32 v176, v80, v81
	v_cvt_pk_bf16_f32 v178, v84, v85
	v_cvt_pk_bf16_f32 v177, v82, v83
	v_cvt_pk_bf16_f32 v179, v86, v87
	ds_read_b64_tr_b16 v[228:229], v166 offset:9728
	ds_read_b64_tr_b16 v[230:231], v166 offset:11776
	s_waitcnt lgkmcnt(12)
	v_mfma_f32_32x32x16_bf16 v[32:47], v[172:175], v[232:235], v[32:47]
	v_exp_f32_e32 v88, v88
	v_exp_f32_e32 v89, v89
	ds_read_b64_tr_b16 v[232:233], v166 offset:12288
	ds_read_b64_tr_b16 v[234:235], v166 offset:14336
	s_waitcnt lgkmcnt(12)
	v_mfma_f32_32x32x16_bf16 v[16:31], v[172:175], v[238:241], v[16:31]
	v_exp_f32_e32 v90, v90
	v_exp_f32_e32 v91, v91
	ds_read_b64_tr_b16 v[238:239], v166 offset:12800
	ds_read_b64_tr_b16 v[240:241], v166 offset:14848
	s_waitcnt lgkmcnt(12)
	v_mfma_f32_32x32x16_bf16 v[0:15], v[172:175], v[212:215], v[0:15]
	v_pk_add_f32 v[254:255], v[254:255], v[88:89]
	v_exp_f32_e32 v92, v92
	v_exp_f32_e32 v93, v93
	ds_read_b64_tr_b16 v[212:213], v166 offset:13312
	ds_read_b64_tr_b16 v[214:215], v166 offset:15360
	s_waitcnt lgkmcnt(12)
	v_mfma_f32_32x32x16_bf16 v[48:63], v[176:179], v[216:219], v[48:63]
	v_pk_add_f32 v[254:255], v[254:255], v[90:91]
	v_exp_f32_e32 v94, v94
	ds_read_b64_tr_b16 v[216:217], v166 offset:13824
	ds_read_b64_tr_b16 v[218:219], v166 offset:15872
	s_waitcnt lgkmcnt(12)
	v_mfma_f32_32x32x16_bf16 v[32:47], v[176:179], v[220:223], v[32:47]
	v_exp_f32_e32 v95, v95
	v_pk_add_f32 v[254:255], v[254:255], v[92:93]
	v_pk_add_f32 v[254:255], v[254:255], v[94:95]
	ds_read_b128 v[184:187], v242 offset:16384
	s_waitcnt lgkmcnt(11)
	v_mfma_f32_32x32x16_bf16 v[16:31], v[176:179], v[224:227], v[16:31]
	v_cvt_pk_bf16_f32 v180, v88, v89
	v_cvt_pk_bf16_f32 v182, v92, v93
	v_cvt_pk_bf16_f32 v181, v90, v91
	v_cvt_pk_bf16_f32 v183, v94, v95
	ds_read_b128 v[188:191], v243 offset:16384
	s_waitcnt lgkmcnt(10)
	v_mfma_f32_32x32x16_bf16 v[0:15], v[176:179], v[228:231], v[0:15]
	s_add_i32 s14, s14, 0x4000
	s_cmp_ge_u32 s14, 0xc000
	s_cselect_b32 s18, 0xc000, 0
	s_sub_i32 s14, s14, s18
	v_add_u32_e32 v166, s14, v165
	ds_read_b128 v[192:195], v244 offset:16384
	s_waitcnt lgkmcnt(9)
	v_mfma_f32_32x32x16_bf16 v[48:63], v[180:183], v[232:235], v[48:63]
	ds_read_b128 v[196:199], v245 offset:16384
	s_waitcnt lgkmcnt(8)
	v_mfma_f32_32x32x16_bf16 v[32:47], v[180:183], v[238:241], v[32:47]
	ds_read_b128 v[200:203], v246 offset:16384
	s_waitcnt lgkmcnt(7)
	v_mfma_f32_32x32x16_bf16 v[16:31], v[180:183], v[212:215], v[16:31]
	ds_read_b128 v[204:207], v247 offset:16384
	s_waitcnt lgkmcnt(6)
	v_mfma_f32_32x32x16_bf16 v[0:15], v[180:183], v[216:219], v[0:15]
	ds_read_b128 v[208:211], v248 offset:16384
	s_waitcnt lgkmcnt(6)
	v_mfma_f32_32x32x16_bf16 v[64:79], v[184:187], v[140:143], 0
	ds_read_b128 v[184:187], v249 offset:16384
	s_waitcnt lgkmcnt(6)
	v_mfma_f32_32x32x16_bf16 v[64:79], v[188:191], v[136:139], v[64:79]
	ds_read_b128 v[188:191], v250 offset:8192
	s_waitcnt lgkmcnt(6)
	v_mfma_f32_32x32x16_bf16 v[64:79], v[192:195], v[132:135], v[64:79]
	ds_read_b128 v[192:195], v251 offset:8192
	s_waitcnt lgkmcnt(6)
	v_mfma_f32_32x32x16_bf16 v[64:79], v[196:199], v[128:131], v[64:79]
	ds_read_b128 v[196:199], v252 offset:8192
	s_waitcnt lgkmcnt(6)
	v_mfma_f32_32x32x16_bf16 v[64:79], v[200:203], v[124:127], v[64:79]
	ds_read_b128 v[200:203], v253 offset:8192
	s_waitcnt lgkmcnt(6)
	v_mfma_f32_32x32x16_bf16 v[64:79], v[204:207], v[120:123], v[64:79]
	ds_read_b128 v[204:207], v242 offset:24576
	s_waitcnt lgkmcnt(6)
	v_mfma_f32_32x32x16_bf16 v[64:79], v[208:211], v[116:119], v[64:79]
	ds_read_b128 v[208:211], v243 offset:24576
	s_waitcnt lgkmcnt(6)
	v_mfma_f32_32x32x16_bf16 v[64:79], v[184:187], v[112:115], v[64:79]
	ds_read_b128 v[184:187], v244 offset:24576
	s_waitcnt lgkmcnt(6)
	v_mfma_f32_32x32x16_bf16 v[64:79], v[188:191], v[96:99], v[64:79]
	ds_read_b128 v[188:191], v245 offset:24576
	s_waitcnt lgkmcnt(6)
	v_mfma_f32_32x32x16_bf16 v[64:79], v[192:195], v[100:103], v[64:79]
	ds_read_b128 v[192:195], v246 offset:24576
	s_waitcnt lgkmcnt(6)
	v_mfma_f32_32x32x16_bf16 v[64:79], v[196:199], v[104:107], v[64:79]
	ds_read_b128 v[196:199], v247 offset:24576
	s_waitcnt lgkmcnt(6)
	v_mfma_f32_32x32x16_bf16 v[64:79], v[200:203], v[108:111], v[64:79]
	ds_read_b128 v[200:203], v248 offset:24576
	s_waitcnt lgkmcnt(6)
	v_mfma_f32_32x32x16_bf16 v[80:95], v[204:207], v[140:143], 0
	ds_read_b128 v[204:207], v249 offset:24576
	s_waitcnt lgkmcnt(6)
	v_mfma_f32_32x32x16_bf16 v[80:95], v[208:211], v[136:139], v[80:95]
	ds_read_b128 v[208:211], v250 offset:12288
	s_waitcnt lgkmcnt(6)
	v_mfma_f32_32x32x16_bf16 v[80:95], v[184:187], v[132:135], v[80:95]
	ds_read_b128 v[184:187], v251 offset:12288
	s_waitcnt lgkmcnt(6)
	v_mfma_f32_32x32x16_bf16 v[80:95], v[188:191], v[128:131], v[80:95]
	v_exp_f32_e32 v64, v64
	v_exp_f32_e32 v65, v65
	v_exp_f32_e32 v66, v66
	ds_read_b128 v[188:191], v252 offset:12288
	s_waitcnt lgkmcnt(6)
	v_mfma_f32_32x32x16_bf16 v[80:95], v[192:195], v[124:127], v[80:95]
	v_exp_f32_e32 v67, v67
	v_pk_add_f32 v[254:255], v[254:255], v[64:65]
	v_exp_f32_e32 v68, v68
	ds_read_b128 v[192:195], v253 offset:12288
	s_waitcnt lgkmcnt(6)
	v_mfma_f32_32x32x16_bf16 v[80:95], v[196:199], v[120:123], v[80:95]
	v_exp_f32_e32 v69, v69
	v_pk_add_f32 v[254:255], v[254:255], v[66:67]
	v_exp_f32_e32 v70, v70
	ds_read_b64_tr_b16 v[212:213], v166 offset:0
	ds_read_b64_tr_b16 v[214:215], v166 offset:2048
	s_waitcnt lgkmcnt(7)
	v_mfma_f32_32x32x16_bf16 v[80:95], v[200:203], v[116:119], v[80:95]
	v_exp_f32_e32 v71, v71
	v_pk_add_f32 v[254:255], v[254:255], v[68:69]
	v_pk_add_f32 v[254:255], v[254:255], v[70:71]
	ds_read_b64_tr_b16 v[216:217], v166 offset:512
	ds_read_b64_tr_b16 v[218:219], v166 offset:2560
	s_waitcnt lgkmcnt(8)
	v_mfma_f32_32x32x16_bf16 v[80:95], v[204:207], v[112:115], v[80:95]
	v_cvt_pk_bf16_f32 v168, v64, v65
	v_cvt_pk_bf16_f32 v170, v68, v69
	v_cvt_pk_bf16_f32 v169, v66, v67
	v_cvt_pk_bf16_f32 v171, v70, v71
	ds_read_b64_tr_b16 v[220:221], v166 offset:1024
	ds_read_b64_tr_b16 v[222:223], v166 offset:3072
	s_waitcnt lgkmcnt(9)
	v_mfma_f32_32x32x16_bf16 v[80:95], v[208:211], v[96:99], v[80:95]
	v_exp_f32_e32 v72, v72
	v_exp_f32_e32 v73, v73
	v_exp_f32_e32 v74, v74
	ds_read_b64_tr_b16 v[224:225], v166 offset:1536
	ds_read_b64_tr_b16 v[226:227], v166 offset:3584
	s_waitcnt lgkmcnt(10)
	v_mfma_f32_32x32x16_bf16 v[80:95], v[184:187], v[100:103], v[80:95]
	v_exp_f32_e32 v75, v75
	v_pk_add_f32 v[254:255], v[254:255], v[72:73]
	v_exp_f32_e32 v76, v76
	v_exp_f32_e32 v77, v77
	ds_read_b64_tr_b16 v[228:229], v166 offset:4096
	ds_read_b64_tr_b16 v[230:231], v166 offset:6144
	s_waitcnt lgkmcnt(11)
	v_mfma_f32_32x32x16_bf16 v[80:95], v[188:191], v[104:107], v[80:95]
	v_pk_add_f32 v[254:255], v[254:255], v[74:75]
	v_exp_f32_e32 v78, v78
	v_exp_f32_e32 v79, v79
	ds_read_b64_tr_b16 v[232:233], v166 offset:4608
	ds_read_b64_tr_b16 v[234:235], v166 offset:6656
	s_waitcnt lgkmcnt(12)
	v_mfma_f32_32x32x16_bf16 v[80:95], v[192:195], v[108:111], v[80:95]
	v_pk_add_f32 v[254:255], v[254:255], v[76:77]
	v_pk_add_f32 v[254:255], v[254:255], v[78:79]
	v_cvt_pk_bf16_f32 v172, v72, v73
	v_cvt_pk_bf16_f32 v174, v76, v77
	v_cvt_pk_bf16_f32 v173, v74, v75
	v_cvt_pk_bf16_f32 v175, v78, v79
	ds_read_b64_tr_b16 v[238:239], v166 offset:5120
	ds_read_b64_tr_b16 v[240:241], v166 offset:7168
	s_waitcnt lgkmcnt(12)
	v_mfma_f32_32x32x16_bf16 v[48:63], v[168:171], v[212:215], v[48:63]
	s_nop 1
	v_exp_f32_e32 v80, v80
	v_exp_f32_e32 v81, v81
	v_exp_f32_e32 v82, v82
	ds_read_b64_tr_b16 v[212:213], v166 offset:5632
	ds_read_b64_tr_b16 v[214:215], v166 offset:7680
	s_waitcnt lgkmcnt(12)
	v_mfma_f32_32x32x16_bf16 v[32:47], v[168:171], v[216:219], v[32:47]
	v_exp_f32_e32 v83, v83
	v_pk_add_f32 v[254:255], v[254:255], v[80:81]
	v_exp_f32_e32 v84, v84
	ds_read_b64_tr_b16 v[216:217], v166 offset:8192
	ds_read_b64_tr_b16 v[218:219], v166 offset:10240
	s_waitcnt lgkmcnt(12)
	v_mfma_f32_32x32x16_bf16 v[16:31], v[168:171], v[220:223], v[16:31]
	v_exp_f32_e32 v85, v85
	v_pk_add_f32 v[254:255], v[254:255], v[82:83]
	v_exp_f32_e32 v86, v86
	ds_read_b64_tr_b16 v[220:221], v166 offset:8704
	ds_read_b64_tr_b16 v[222:223], v166 offset:10752
	s_waitcnt lgkmcnt(12)
	v_mfma_f32_32x32x16_bf16 v[0:15], v[168:171], v[224:227], v[0:15]
	v_exp_f32_e32 v87, v87
	v_pk_add_f32 v[254:255], v[254:255], v[84:85]
	v_pk_add_f32 v[254:255], v[254:255], v[86:87]
	ds_read_b64_tr_b16 v[224:225], v166 offset:9216
	ds_read_b64_tr_b16 v[226:227], v166 offset:11264
	s_waitcnt lgkmcnt(12)
	v_mfma_f32_32x32x16_bf16 v[48:63], v[172:175], v[228:231], v[48:63]
	v_cvt_pk_bf16_f32 v176, v80, v81
	v_cvt_pk_bf16_f32 v178, v84, v85
	v_cvt_pk_bf16_f32 v177, v82, v83
	v_cvt_pk_bf16_f32 v179, v86, v87
	ds_read_b64_tr_b16 v[228:229], v166 offset:9728
	ds_read_b64_tr_b16 v[230:231], v166 offset:11776
	s_waitcnt lgkmcnt(12)
	v_mfma_f32_32x32x16_bf16 v[32:47], v[172:175], v[232:235], v[32:47]
	v_exp_f32_e32 v88, v88
	v_exp_f32_e32 v89, v89
	ds_read_b64_tr_b16 v[232:233], v166 offset:12288
	ds_read_b64_tr_b16 v[234:235], v166 offset:14336
	s_waitcnt lgkmcnt(12)
	v_mfma_f32_32x32x16_bf16 v[16:31], v[172:175], v[238:241], v[16:31]
	v_exp_f32_e32 v90, v90
	v_exp_f32_e32 v91, v91
	ds_read_b64_tr_b16 v[238:239], v166 offset:12800
	ds_read_b64_tr_b16 v[240:241], v166 offset:14848
	s_waitcnt lgkmcnt(12)
	v_mfma_f32_32x32x16_bf16 v[0:15], v[172:175], v[212:215], v[0:15]
	v_pk_add_f32 v[254:255], v[254:255], v[88:89]
	v_exp_f32_e32 v92, v92
	v_exp_f32_e32 v93, v93
	ds_read_b64_tr_b16 v[212:213], v166 offset:13312
	ds_read_b64_tr_b16 v[214:215], v166 offset:15360
	s_waitcnt lgkmcnt(12)
	v_mfma_f32_32x32x16_bf16 v[48:63], v[176:179], v[216:219], v[48:63]
	v_pk_add_f32 v[254:255], v[254:255], v[90:91]
	v_exp_f32_e32 v94, v94
	ds_read_b64_tr_b16 v[216:217], v166 offset:13824
	ds_read_b64_tr_b16 v[218:219], v166 offset:15872
	s_waitcnt lgkmcnt(12)
	v_mfma_f32_32x32x16_bf16 v[32:47], v[176:179], v[220:223], v[32:47]
	v_exp_f32_e32 v95, v95
	v_pk_add_f32 v[254:255], v[254:255], v[92:93]
	v_pk_add_f32 v[254:255], v[254:255], v[94:95]
	s_waitcnt lgkmcnt(10)
	v_mfma_f32_32x32x16_bf16 v[16:31], v[176:179], v[224:227], v[16:31]
	v_cvt_pk_bf16_f32 v180, v88, v89
	v_cvt_pk_bf16_f32 v182, v92, v93
	v_cvt_pk_bf16_f32 v181, v90, v91
	v_cvt_pk_bf16_f32 v183, v94, v95
	s_waitcnt lgkmcnt(8)
	v_mfma_f32_32x32x16_bf16 v[0:15], v[176:179], v[228:231], v[0:15]
	s_waitcnt lgkmcnt(6)
	v_mfma_f32_32x32x16_bf16 v[48:63], v[180:183], v[232:235], v[48:63]
	s_waitcnt lgkmcnt(4)
	v_mfma_f32_32x32x16_bf16 v[32:47], v[180:183], v[238:241], v[32:47]
	s_waitcnt lgkmcnt(2)
	v_mfma_f32_32x32x16_bf16 v[16:31], v[180:183], v[212:215], v[16:31]
	s_waitcnt lgkmcnt(0)
	v_mfma_f32_32x32x16_bf16 v[0:15], v[180:183], v[216:219], v[0:15]
	v_add_f32_e32 v112, v254, v255
	v_mov_b32_e32 v113, 0
	v_mov_b32_e32 v115, 0
	v_mov_b32_e32 v114, v112
	v_mov_b32_e32 v146, 0
	s_nop 0
	v_permlane32_swap_b32_e32 v112, v114
	s_and_b32 s0, s0, 0x3fffffc0
	s_lshl_b32 s0, s0, 2
	s_add_i32 s5, s0, 0
	s_add_i32 s5, s5, 0x18000
	s_setprio 0
	v_cmp_gt_u32_e32 vcc, 32, v149
	s_and_saveexec_b64 s[0:1], vcc
	s_cbranch_execz .LBB0_781
	v_pk_add_f32 v[64:65], v[112:113], v[114:115]
	v_lshl_add_u32 v66, v162, 2, s5
	v_add_f32_e32 v64, v146, v64
	v_add_f32_e32 v64, v64, v65
	ds_write_b32 v66, v64
	s_branch .LBB0_781
